# combined: v12 attention edits + attention epilogue gate-load prefetch + HGRN-A gate-phase LDS read hoisting + HGRN-B permlane sum-reduce
# baseline (speedup 1.0000x reference)
; __device__ __forceinline__ float bf2f(short b) { return __uint_as_float(((unsigned)(unsigned short)b) << 16); }
; __device__ __forceinline__ u32x2 pack4(f32x4 a) { u32x2 w = {pk2(a[0], a[1]), pk2(a[2], a[3])}; return w; }
; __device__ __forceinline__ float fexp(float x) { return __builtin_amdgcn_exp2f(x * 1.4426950408889634f); }
; __device__ __forceinline__ void attn_phase(unsigned char* lds, const Params& p, int jl, const bf16_t* proj, bf16_t* mix, int blk, int G, int tid) {
;     ...
;             float l = l_run[qt]; l += __shfl_xor(l, 16); l += __shfl_xor(l, 32);
;             if (!samp || w < 1) {
;                 const float inv = 1.f / l; const int row = qrow0 + (samp ? 0 : w * 32) + qt * 16 + fr;
;                 const bf16_t* gp = proj + (size_t)row * N4 + 6144 + h * 128 + fq * 4; bf16_t* mp = mix + (size_t)row * DM + h * 128 + fq * 4;
; #pragma unroll
;                 for (int dt = 0; dt < 8; ++dt) { const bf16x4 gv = *(const bf16x4*)(gp + dt * 16); f32x4 ov;
; #pragma unroll
;                     for (int j = 0; j < 4; ++j) { const float gg = bf2f(gv[j]); ov[j] = o[qt][dt][j] * inv * (gg * __builtin_amdgcn_rcpf(1.f + fexp(-gg))); }
;                     *(u32x2*)(mp + dt * 16) = pack4(ov); }
.LBB0_218:
	v_and_b32_e32 v2, 64, v213
	v_xor_b32_e32 v0, 16, v213
	v_add_u32_e32 v2, 64, v2
	v_cmp_lt_i32_e32 vcc, v0, v2
	s_lshl_b32 s28, s11, 1
	s_nop 0
	v_cndmask_b32_e32 v0, v213, v0, vcc
	v_lshlrev_b32_e32 v55, 2, v0
	ds_bpermute_b32 v3, v55, v205
	v_xor_b32_e32 v0, 32, v213
	v_cmp_lt_i32_e32 vcc, v0, v2
	s_waitcnt lgkmcnt(0)
	v_add_f32_e32 v53, v205, v3
	v_cndmask_b32_e32 v0, v213, v0, vcc
	v_lshlrev_b32_e32 v60, 2, v0
	ds_bpermute_b32 v54, v60, v53
	v_cndmask_b32_e64 v0, v192, 0, s[6:7]
	v_or_b32_e32 v0, v0, v165
	v_add_u32_e32 v52, s27, v0
	v_lshl_add_u64 v[2:3], v[166:167], 0, s[28:29]
	v_lshlrev_b32_e32 v0, 1, v164
	s_and_saveexec_b64 s[4:5], s[2:3]
	s_cbranch_execz .LBB0_220
	s_waitcnt lgkmcnt(0)
	v_add_f32_e32 v53, v53, v54
	v_div_scale_f32 v54, s[6:7], v53, v53, 1.0
	v_rcp_f32_e32 v56, v54
	s_mov_b64 s[6:7], 0x3000
	v_fma_f32 v57, -v54, v56, 1.0
	v_fmac_f32_e32 v56, v57, v56
	v_div_scale_f32 v57, vcc, 1.0, v53, 1.0
	v_mul_f32_e32 v58, v57, v56
	v_fma_f32 v59, -v54, v58, v57
	v_fmac_f32_e32 v58, v59, v56
	v_fma_f32 v54, -v54, v58, v57
	v_div_fmas_f32 v54, v54, v56, v58
	v_div_fixup_f32 v54, v54, v53, 1.0
	v_ashrrev_i32_e32 v53, 31, v52
	v_lshlrev_b64 v[56:57], 14, v[52:53]
	v_lshl_add_u64 v[56:57], s[84:85], 0, v[56:57]
	v_lshl_add_u64 v[56:57], v[56:57], 0, s[28:29]
	v_lshl_add_u64 v[62:63], v[56:57], 0, v[0:1]
	v_lshl_add_u64 v[58:59], v[62:63], 0, s[6:7]
	s_movk_i32 s6, 0x3000
	v_add_co_u32_e32 v62, vcc, s6, v62
	v_lshlrev_b64 v[56:57], 12, v[52:53]
	s_nop 0
	v_addc_co_u32_e32 v63, vcc, 0, v63, vcc
	global_load_dwordx2 v[230:231], v[62:63], off
	global_load_dwordx2 v[232:233], v[58:59], off offset:32
	global_load_dwordx2 v[234:235], v[58:59], off offset:64
	global_load_dwordx2 v[236:237], v[58:59], off offset:96
	global_load_dwordx2 v[238:239], v[58:59], off offset:128
	global_load_dwordx2 v[240:241], v[58:59], off offset:160
	global_load_dwordx2 v[242:243], v[58:59], off offset:192
	global_load_dwordx2 v[244:245], v[58:59], off offset:224
	v_pk_mul_f32 v[68:69], v[104:105], v[54:55] op_sel_hi:[1,0]
	v_lshl_add_u64 v[56:57], v[2:3], 0, v[56:57]
	v_pk_mul_f32 v[48:49], v[48:49], v[54:55] op_sel_hi:[1,0]
	v_pk_mul_f32 v[50:51], v[50:51], v[54:55] op_sel_hi:[1,0]
	v_pk_mul_f32 v[44:45], v[44:45], v[54:55] op_sel_hi:[1,0]
	v_pk_mul_f32 v[46:47], v[46:47], v[54:55] op_sel_hi:[1,0]
	v_pk_mul_f32 v[40:41], v[40:41], v[54:55] op_sel_hi:[1,0]
	v_pk_mul_f32 v[42:43], v[42:43], v[54:55] op_sel_hi:[1,0]
	v_pk_mul_f32 v[36:37], v[36:37], v[54:55] op_sel_hi:[1,0]
	v_pk_mul_f32 v[38:39], v[38:39], v[54:55] op_sel_hi:[1,0]
	s_waitcnt vmcnt(0)
	v_mov_b32_e32 v62, v230
	v_mov_b32_e32 v63, v231
	v_lshlrev_b32_e32 v64, 16, v62
	v_mul_f32_e32 v53, 0xbfb8aa3b, v64
	v_exp_f32_e32 v53, v53
	v_and_b32_e32 v65, 0xffff0000, v62
	v_add_f32_e32 v53, 1.0, v53
	v_rcp_f32_e32 v66, v53
	v_mul_f32_e32 v53, 0xbfb8aa3b, v65
	v_exp_f32_e32 v53, v53
	s_nop 0
	v_add_f32_e32 v53, 1.0, v53
	v_rcp_f32_e32 v67, v53
	s_nop 0
	v_pk_mul_f32 v[64:65], v[66:67], v[64:65]
	v_lshlrev_b32_e32 v66, 16, v63
	v_mul_f32_e32 v53, 0xbfb8aa3b, v66
	v_exp_f32_e32 v53, v53
	v_and_b32_e32 v67, 0xffff0000, v63
	v_pk_mul_f32 v[64:65], v[68:69], v[64:65]
	v_pk_mul_f32 v[68:69], v[106:107], v[54:55] op_sel_hi:[1,0]
	v_add_f32_e32 v53, 1.0, v53
	v_rcp_f32_e32 v62, v53
	v_mul_f32_e32 v53, 0xbfb8aa3b, v67
	v_exp_f32_e32 v53, v53
	v_cvt_pk_bf16_f32 v64, v64, v65
	v_add_f32_e32 v53, 1.0, v53
	v_rcp_f32_e32 v63, v53
	s_nop 0
	v_pk_mul_f32 v[62:63], v[62:63], v[66:67]
	s_nop 0
	v_pk_mul_f32 v[62:63], v[68:69], v[62:63]
	v_pk_mul_f32 v[68:69], v[96:97], v[54:55] op_sel_hi:[1,0]
	v_cvt_pk_bf16_f32 v65, v62, v63
	v_mov_b32_e32 v62, v232
	v_mov_b32_e32 v63, v233
	s_nop 0
	global_store_dwordx2 v[56:57], v[64:65], off
	v_lshlrev_b32_e32 v64, 16, v62
	v_mul_f32_e32 v53, 0xbfb8aa3b, v64
	v_exp_f32_e32 v53, v53
	v_and_b32_e32 v65, 0xffff0000, v62
	v_add_f32_e32 v53, 1.0, v53
	v_rcp_f32_e32 v66, v53
	v_mul_f32_e32 v53, 0xbfb8aa3b, v65
	v_exp_f32_e32 v53, v53
	s_nop 0
	v_add_f32_e32 v53, 1.0, v53
	v_rcp_f32_e32 v67, v53
	s_nop 0
	v_pk_mul_f32 v[64:65], v[66:67], v[64:65]
	v_lshlrev_b32_e32 v66, 16, v63
	v_mul_f32_e32 v53, 0xbfb8aa3b, v66
	v_exp_f32_e32 v53, v53
	v_and_b32_e32 v67, 0xffff0000, v63
	v_pk_mul_f32 v[64:65], v[68:69], v[64:65]
	v_pk_mul_f32 v[68:69], v[98:99], v[54:55] op_sel_hi:[1,0]
	v_add_f32_e32 v53, 1.0, v53
	v_rcp_f32_e32 v62, v53
	v_mul_f32_e32 v53, 0xbfb8aa3b, v67
	v_exp_f32_e32 v53, v53
	v_cvt_pk_bf16_f32 v64, v64, v65
	v_add_f32_e32 v53, 1.0, v53
	v_rcp_f32_e32 v63, v53
	s_nop 0
	v_pk_mul_f32 v[62:63], v[62:63], v[66:67]
	s_nop 0
	v_pk_mul_f32 v[62:63], v[68:69], v[62:63]
	v_pk_mul_f32 v[68:69], v[88:89], v[54:55] op_sel_hi:[1,0]
	v_cvt_pk_bf16_f32 v65, v62, v63
	v_mov_b32_e32 v62, v234
	v_mov_b32_e32 v63, v235
	s_nop 0
	global_store_dwordx2 v[56:57], v[64:65], off offset:32
	v_lshlrev_b32_e32 v64, 16, v62
	v_mul_f32_e32 v53, 0xbfb8aa3b, v64
	v_exp_f32_e32 v53, v53
	v_and_b32_e32 v65, 0xffff0000, v62
	v_add_f32_e32 v53, 1.0, v53
	v_rcp_f32_e32 v66, v53
	v_mul_f32_e32 v53, 0xbfb8aa3b, v65
	v_exp_f32_e32 v53, v53
	s_nop 0
	v_add_f32_e32 v53, 1.0, v53
	v_rcp_f32_e32 v67, v53
	s_nop 0
	v_pk_mul_f32 v[64:65], v[66:67], v[64:65]
	v_lshlrev_b32_e32 v66, 16, v63
	v_mul_f32_e32 v53, 0xbfb8aa3b, v66
	v_exp_f32_e32 v53, v53
	v_and_b32_e32 v67, 0xffff0000, v63
	v_pk_mul_f32 v[64:65], v[68:69], v[64:65]
	v_pk_mul_f32 v[68:69], v[90:91], v[54:55] op_sel_hi:[1,0]
	v_add_f32_e32 v53, 1.0, v53
	v_rcp_f32_e32 v62, v53
	v_mul_f32_e32 v53, 0xbfb8aa3b, v67
	v_exp_f32_e32 v53, v53
	v_cvt_pk_bf16_f32 v64, v64, v65
	v_add_f32_e32 v53, 1.0, v53
	v_rcp_f32_e32 v63, v53
	s_nop 0
	v_pk_mul_f32 v[62:63], v[62:63], v[66:67]
; __device__ __forceinline__ float bf2f(short b) { return __uint_as_float(((unsigned)(unsigned short)b) << 16); }
; __device__ __forceinline__ u32x2 pack4(f32x4 a) { u32x2 w = {pk2(a[0], a[1]), pk2(a[2], a[3])}; return w; }
; __device__ __forceinline__ float fexp(float x) { return __builtin_amdgcn_exp2f(x * 1.4426950408889634f); }
; __device__ __forceinline__ void attn_phase(unsigned char* lds, const Params& p, int jl, const bf16_t* proj, bf16_t* mix, int blk, int G, int tid) {
;     ...
;                 for (int dt = 0; dt < 8; ++dt) { const bf16x4 gv = *(const bf16x4*)(gp + dt * 16); f32x4 ov;
; #pragma unroll
;                     for (int j = 0; j < 4; ++j) { const float gg = bf2f(gv[j]); ov[j] = o[qt][dt][j] * inv * (gg * __builtin_amdgcn_rcpf(1.f + fexp(-gg))); }
;                     *(u32x2*)(mp + dt * 16) = pack4(ov); }
	s_nop 0
	v_pk_mul_f32 v[62:63], v[68:69], v[62:63]
	v_pk_mul_f32 v[68:69], v[84:85], v[54:55] op_sel_hi:[1,0]
	v_cvt_pk_bf16_f32 v65, v62, v63
	v_mov_b32_e32 v62, v236
	v_mov_b32_e32 v63, v237
	s_nop 0
	global_store_dwordx2 v[56:57], v[64:65], off offset:64
	v_lshlrev_b32_e32 v64, 16, v62
	v_mul_f32_e32 v53, 0xbfb8aa3b, v64
	v_exp_f32_e32 v53, v53
	v_and_b32_e32 v65, 0xffff0000, v62
	v_add_f32_e32 v53, 1.0, v53
	v_rcp_f32_e32 v66, v53
	v_mul_f32_e32 v53, 0xbfb8aa3b, v65
	v_exp_f32_e32 v53, v53
	s_nop 0
	v_add_f32_e32 v53, 1.0, v53
	v_rcp_f32_e32 v67, v53
	s_nop 0
	v_pk_mul_f32 v[64:65], v[66:67], v[64:65]
	v_lshlrev_b32_e32 v66, 16, v63
	v_mul_f32_e32 v53, 0xbfb8aa3b, v66
	v_exp_f32_e32 v53, v53
	v_and_b32_e32 v67, 0xffff0000, v63
	v_pk_mul_f32 v[64:65], v[68:69], v[64:65]
	v_pk_mul_f32 v[68:69], v[86:87], v[54:55] op_sel_hi:[1,0]
	v_add_f32_e32 v53, 1.0, v53
	v_rcp_f32_e32 v62, v53
	v_mul_f32_e32 v53, 0xbfb8aa3b, v67
	v_exp_f32_e32 v53, v53
	v_cvt_pk_bf16_f32 v64, v64, v65
	v_add_f32_e32 v53, 1.0, v53
	v_rcp_f32_e32 v63, v53
	s_nop 0
	v_pk_mul_f32 v[62:63], v[62:63], v[66:67]
	s_nop 0
	v_pk_mul_f32 v[62:63], v[68:69], v[62:63]
	s_nop 0
	v_cvt_pk_bf16_f32 v65, v62, v63
	v_mov_b32_e32 v62, v238
	v_mov_b32_e32 v63, v239
	s_nop 0
	global_store_dwordx2 v[56:57], v[64:65], off offset:96
	v_lshlrev_b32_e32 v64, 16, v62
	v_mul_f32_e32 v53, 0xbfb8aa3b, v64
	v_exp_f32_e32 v53, v53
	v_and_b32_e32 v65, 0xffff0000, v62
	v_add_f32_e32 v53, 1.0, v53
	v_rcp_f32_e32 v66, v53
	v_mul_f32_e32 v53, 0xbfb8aa3b, v65
	v_exp_f32_e32 v53, v53
	s_nop 0
	v_add_f32_e32 v53, 1.0, v53
	v_rcp_f32_e32 v67, v53
	s_nop 0
	v_pk_mul_f32 v[64:65], v[66:67], v[64:65]
	s_nop 0
	v_pk_mul_f32 v[48:49], v[48:49], v[64:65]
	v_lshlrev_b32_e32 v64, 16, v63
	v_mul_f32_e32 v53, 0xbfb8aa3b, v64
	v_exp_f32_e32 v53, v53
	v_and_b32_e32 v65, 0xffff0000, v63
	v_cvt_pk_bf16_f32 v48, v48, v49
	v_add_f32_e32 v53, 1.0, v53
	v_rcp_f32_e32 v62, v53
	v_mul_f32_e32 v53, 0xbfb8aa3b, v65
	v_exp_f32_e32 v53, v53
	s_nop 0
	v_add_f32_e32 v53, 1.0, v53
	v_rcp_f32_e32 v63, v53
	s_nop 0
	v_pk_mul_f32 v[62:63], v[62:63], v[64:65]
	s_nop 0
	v_pk_mul_f32 v[50:51], v[50:51], v[62:63]
	s_nop 0
	v_cvt_pk_bf16_f32 v49, v50, v51
	global_store_dwordx2 v[56:57], v[48:49], off offset:128
	v_mov_b32_e32 v48, v240
	v_mov_b32_e32 v49, v241
	v_lshlrev_b32_e32 v50, 16, v48
	v_and_b32_e32 v51, 0xffff0000, v48
	v_mul_f32_e32 v48, 0xbfb8aa3b, v50
	v_exp_f32_e32 v48, v48
	s_nop 0
	v_add_f32_e32 v48, 1.0, v48
	v_rcp_f32_e32 v62, v48
	v_mul_f32_e32 v48, 0xbfb8aa3b, v51
	v_exp_f32_e32 v48, v48
	s_nop 0
	v_add_f32_e32 v48, 1.0, v48
	v_rcp_f32_e32 v63, v48
	s_nop 0
	v_pk_mul_f32 v[50:51], v[62:63], v[50:51]
	s_nop 0
	v_pk_mul_f32 v[44:45], v[44:45], v[50:51]
	v_and_b32_e32 v51, 0xffff0000, v49
	v_lshlrev_b32_e32 v50, 16, v49
	v_mul_f32_e32 v48, 0xbfb8aa3b, v50
	v_mul_f32_e32 v49, 0xbfb8aa3b, v51
	v_exp_f32_e32 v48, v48
	v_exp_f32_e32 v49, v49
	v_cvt_pk_bf16_f32 v44, v44, v45
	v_add_f32_e32 v48, 1.0, v48
	v_add_f32_e32 v49, 1.0, v49
	v_rcp_f32_e32 v48, v48
	v_rcp_f32_e32 v49, v49
	s_nop 0
	v_pk_mul_f32 v[48:49], v[48:49], v[50:51]
	s_nop 0
	v_pk_mul_f32 v[46:47], v[46:47], v[48:49]
	s_nop 0
	v_cvt_pk_bf16_f32 v45, v46, v47
	global_store_dwordx2 v[56:57], v[44:45], off offset:160
	v_mov_b32_e32 v44, v242
	v_mov_b32_e32 v45, v243
	v_lshlrev_b32_e32 v46, 16, v44
	v_and_b32_e32 v47, 0xffff0000, v44
	v_mul_f32_e32 v44, 0xbfb8aa3b, v46
	v_exp_f32_e32 v44, v44
	s_nop 0
	v_add_f32_e32 v44, 1.0, v44
	v_rcp_f32_e32 v48, v44
	v_mul_f32_e32 v44, 0xbfb8aa3b, v47
	v_exp_f32_e32 v44, v44
	s_nop 0
	v_add_f32_e32 v44, 1.0, v44
	v_rcp_f32_e32 v49, v44
	s_nop 0
	v_pk_mul_f32 v[46:47], v[48:49], v[46:47]
	s_nop 0
	v_pk_mul_f32 v[40:41], v[40:41], v[46:47]
	v_and_b32_e32 v47, 0xffff0000, v45
	v_lshlrev_b32_e32 v46, 16, v45
	v_mul_f32_e32 v44, 0xbfb8aa3b, v46
	v_mul_f32_e32 v45, 0xbfb8aa3b, v47
	v_exp_f32_e32 v44, v44
	v_exp_f32_e32 v45, v45
	v_cvt_pk_bf16_f32 v40, v40, v41
	v_add_f32_e32 v44, 1.0, v44
	v_add_f32_e32 v45, 1.0, v45
	v_rcp_f32_e32 v44, v44
	v_rcp_f32_e32 v45, v45
	s_nop 0
	v_pk_mul_f32 v[44:45], v[44:45], v[46:47]
	s_nop 0
	v_pk_mul_f32 v[42:43], v[42:43], v[44:45]
	s_nop 0
	v_cvt_pk_bf16_f32 v41, v42, v43
	global_store_dwordx2 v[56:57], v[40:41], off offset:192
	v_mov_b32_e32 v40, v244
	v_mov_b32_e32 v41, v245
	v_lshlrev_b32_e32 v42, 16, v40
	v_and_b32_e32 v43, 0xffff0000, v40
	v_mul_f32_e32 v40, 0xbfb8aa3b, v42
	v_exp_f32_e32 v40, v40
	s_nop 0
	v_add_f32_e32 v40, 1.0, v40
	v_rcp_f32_e32 v44, v40
	v_mul_f32_e32 v40, 0xbfb8aa3b, v43
	v_exp_f32_e32 v40, v40
	s_nop 0
	v_add_f32_e32 v40, 1.0, v40
	v_rcp_f32_e32 v45, v40
	s_nop 0
	v_pk_mul_f32 v[42:43], v[44:45], v[42:43]
	s_nop 0
	v_pk_mul_f32 v[36:37], v[36:37], v[42:43]
	v_and_b32_e32 v43, 0xffff0000, v41
	v_lshlrev_b32_e32 v42, 16, v41
	v_mul_f32_e32 v40, 0xbfb8aa3b, v42
	v_mul_f32_e32 v41, 0xbfb8aa3b, v43
	v_exp_f32_e32 v40, v40
	v_exp_f32_e32 v41, v41
	v_cvt_pk_bf16_f32 v36, v36, v37
	v_add_f32_e32 v40, 1.0, v40
	v_add_f32_e32 v41, 1.0, v41
	v_rcp_f32_e32 v40, v40
	v_rcp_f32_e32 v41, v41
	s_nop 0
	v_pk_mul_f32 v[40:41], v[40:41], v[42:43]
	s_nop 0
	v_pk_mul_f32 v[38:39], v[38:39], v[40:41]
	s_nop 0
	v_cvt_pk_bf16_f32 v37, v38, v39
	global_store_dwordx2 v[56:57], v[36:37], off offset:224
; __device__ __forceinline__ float bf2f(short b) { return __uint_as_float(((unsigned)(unsigned short)b) << 16); }
; __device__ __forceinline__ u32x2 pack4(f32x4 a) { u32x2 w = {pk2(a[0], a[1]), pk2(a[2], a[3])}; return w; }
; __device__ __forceinline__ float fexp(float x) { return __builtin_amdgcn_exp2f(x * 1.4426950408889634f); }
; __device__ __forceinline__ void attn_phase(unsigned char* lds, const Params& p, int jl, const bf16_t* proj, bf16_t* mix, int blk, int G, int tid) {
;     ...
;             float l = l_run[qt]; l += __shfl_xor(l, 16); l += __shfl_xor(l, 32);
;             if (!samp || w < 1) {
;                 const float inv = 1.f / l; const int row = qrow0 + (samp ? 0 : w * 32) + qt * 16 + fr;
;                 const bf16_t* gp = proj + (size_t)row * N4 + 6144 + h * 128 + fq * 4; bf16_t* mp = mix + (size_t)row * DM + h * 128 + fq * 4;
; #pragma unroll
;                 for (int dt = 0; dt < 8; ++dt) { const bf16x4 gv = *(const bf16x4*)(gp + dt * 16); f32x4 ov;
; #pragma unroll
;                     for (int j = 0; j < 4; ++j) { const float gg = bf2f(gv[j]); ov[j] = o[qt][dt][j] * inv * (gg * __builtin_amdgcn_rcpf(1.f + fexp(-gg))); }
;                     *(u32x2*)(mp + dt * 16) = pack4(ov); }
.LBB0_220:
	s_or_b64 exec, exec, s[4:5]
	ds_bpermute_b32 v36, v55, v201
	s_waitcnt lgkmcnt(0)
	v_add_f32_e32 v36, v201, v36
	ds_bpermute_b32 v37, v60, v36
	s_and_saveexec_b64 s[4:5], s[2:3]
	s_cbranch_execz .LBB0_132
	s_waitcnt lgkmcnt(0)
	v_add_f32_e32 v36, v36, v37
	v_div_scale_f32 v37, s[2:3], v36, v36, 1.0
	v_rcp_f32_e32 v38, v37
	s_mov_b64 s[2:3], 0x3000
	v_fma_f32 v39, -v37, v38, 1.0
	v_fmac_f32_e32 v38, v39, v38
	v_div_scale_f32 v39, vcc, 1.0, v36, 1.0
	v_mul_f32_e32 v40, v39, v38
	v_fma_f32 v41, -v37, v40, v39
	v_fmac_f32_e32 v40, v41, v38
	v_fma_f32 v37, -v37, v40, v39
	v_div_fmas_f32 v37, v37, v38, v40
	v_add_u32_e32 v40, 16, v52
	v_ashrrev_i32_e32 v41, 31, v40
	v_lshlrev_b64 v[38:39], 14, v[40:41]
	v_lshl_add_u64 v[38:39], s[84:85], 0, v[38:39]
	v_lshl_add_u64 v[38:39], v[38:39], 0, s[28:29]
	v_lshl_add_u64 v[42:43], v[38:39], 0, v[0:1]
	v_lshl_add_u64 v[38:39], v[42:43], 0, s[2:3]
	v_lshlrev_b64 v[40:41], 12, v[40:41]
	s_movk_i32 s2, 0x3000
	v_lshl_add_u64 v[2:3], v[2:3], 0, v[40:41]
	v_add_co_u32_e32 v40, vcc, s2, v42
	v_div_fixup_f32 v36, v37, v36, 1.0
	s_nop 0
	v_addc_co_u32_e32 v41, vcc, 0, v43, vcc
	global_load_dwordx2 v[230:231], v[40:41], off
	global_load_dwordx2 v[232:233], v[38:39], off offset:32
	global_load_dwordx2 v[234:235], v[38:39], off offset:64
	global_load_dwordx2 v[236:237], v[38:39], off offset:96
	global_load_dwordx2 v[238:239], v[38:39], off offset:128
	global_load_dwordx2 v[240:241], v[38:39], off offset:160
	global_load_dwordx2 v[242:243], v[38:39], off offset:192
	global_load_dwordx2 v[244:245], v[38:39], off offset:224
	v_pk_mul_f32 v[32:33], v[32:33], v[36:37] op_sel_hi:[1,0]
	v_pk_mul_f32 v[34:35], v[34:35], v[36:37] op_sel_hi:[1,0]
	v_pk_mul_f32 v[28:29], v[28:29], v[36:37] op_sel_hi:[1,0]
	v_pk_mul_f32 v[30:31], v[30:31], v[36:37] op_sel_hi:[1,0]
	v_pk_mul_f32 v[24:25], v[24:25], v[36:37] op_sel_hi:[1,0]
	v_pk_mul_f32 v[26:27], v[26:27], v[36:37] op_sel_hi:[1,0]
	v_pk_mul_f32 v[20:21], v[20:21], v[36:37] op_sel_hi:[1,0]
	v_pk_mul_f32 v[22:23], v[22:23], v[36:37] op_sel_hi:[1,0]
	v_pk_mul_f32 v[16:17], v[16:17], v[36:37] op_sel_hi:[1,0]
	v_pk_mul_f32 v[18:19], v[18:19], v[36:37] op_sel_hi:[1,0]
	v_pk_mul_f32 v[12:13], v[12:13], v[36:37] op_sel_hi:[1,0]
	v_pk_mul_f32 v[14:15], v[14:15], v[36:37] op_sel_hi:[1,0]
	v_pk_mul_f32 v[8:9], v[8:9], v[36:37] op_sel_hi:[1,0]
	v_pk_mul_f32 v[10:11], v[10:11], v[36:37] op_sel_hi:[1,0]
	v_pk_mul_f32 v[4:5], v[4:5], v[36:37] op_sel_hi:[1,0]
	v_pk_mul_f32 v[6:7], v[6:7], v[36:37] op_sel_hi:[1,0]
	s_waitcnt vmcnt(0)
	v_mov_b32_e32 v40, v230
	v_mov_b32_e32 v41, v231
	v_lshlrev_b32_e32 v42, 16, v40
	v_mul_f32_e32 v0, 0xbfb8aa3b, v42
	v_exp_f32_e32 v0, v0
	v_and_b32_e32 v43, 0xffff0000, v40
	v_add_f32_e32 v0, 1.0, v0
	v_rcp_f32_e32 v44, v0
	v_mul_f32_e32 v0, 0xbfb8aa3b, v43
	v_exp_f32_e32 v0, v0
	s_nop 0
	v_add_f32_e32 v0, 1.0, v0
	v_rcp_f32_e32 v45, v0
	s_nop 0
	v_pk_mul_f32 v[42:43], v[44:45], v[42:43]
	s_nop 0
	v_pk_mul_f32 v[32:33], v[32:33], v[42:43]
	v_lshlrev_b32_e32 v42, 16, v41
	v_mul_f32_e32 v0, 0xbfb8aa3b, v42
	v_exp_f32_e32 v0, v0
	v_and_b32_e32 v43, 0xffff0000, v41
	v_cvt_pk_bf16_f32 v32, v32, v33
	v_add_f32_e32 v0, 1.0, v0
	v_rcp_f32_e32 v40, v0
	v_mul_f32_e32 v0, 0xbfb8aa3b, v43
	v_exp_f32_e32 v0, v0
	s_nop 0
	v_add_f32_e32 v0, 1.0, v0
	v_rcp_f32_e32 v41, v0
	s_nop 0
	v_pk_mul_f32 v[40:41], v[40:41], v[42:43]
	s_nop 0
	v_pk_mul_f32 v[34:35], v[34:35], v[40:41]
	s_nop 0
	v_cvt_pk_bf16_f32 v33, v34, v35
	global_store_dwordx2 v[2:3], v[32:33], off
	v_mov_b32_e32 v32, v232
	v_mov_b32_e32 v33, v233
	v_lshlrev_b32_e32 v34, 16, v32
	v_mul_f32_e32 v0, 0xbfb8aa3b, v34
	v_exp_f32_e32 v0, v0
	v_and_b32_e32 v35, 0xffff0000, v32
	v_add_f32_e32 v0, 1.0, v0
	v_rcp_f32_e32 v40, v0
	v_mul_f32_e32 v0, 0xbfb8aa3b, v35
	v_exp_f32_e32 v0, v0
	s_nop 0
	v_add_f32_e32 v0, 1.0, v0
	v_rcp_f32_e32 v41, v0
	s_nop 0
	v_pk_mul_f32 v[34:35], v[40:41], v[34:35]
	s_nop 0
	v_pk_mul_f32 v[28:29], v[28:29], v[34:35]
	v_lshlrev_b32_e32 v34, 16, v33
	v_mul_f32_e32 v0, 0xbfb8aa3b, v34
	v_exp_f32_e32 v0, v0
	v_and_b32_e32 v35, 0xffff0000, v33
	v_cvt_pk_bf16_f32 v28, v28, v29
	v_add_f32_e32 v0, 1.0, v0
	v_rcp_f32_e32 v32, v0
	v_mul_f32_e32 v0, 0xbfb8aa3b, v35
	v_exp_f32_e32 v0, v0
	s_nop 0
	v_add_f32_e32 v0, 1.0, v0
	v_rcp_f32_e32 v33, v0
	s_nop 0
	v_pk_mul_f32 v[32:33], v[32:33], v[34:35]
	s_nop 0
	v_pk_mul_f32 v[30:31], v[30:31], v[32:33]
	s_nop 0
	v_cvt_pk_bf16_f32 v29, v30, v31
	global_store_dwordx2 v[2:3], v[28:29], off offset:32
	v_mov_b32_e32 v28, v234
	v_mov_b32_e32 v29, v235
	v_lshlrev_b32_e32 v30, 16, v28
	v_mul_f32_e32 v0, 0xbfb8aa3b, v30
	v_exp_f32_e32 v0, v0
	v_and_b32_e32 v31, 0xffff0000, v28
	v_add_f32_e32 v0, 1.0, v0
	v_rcp_f32_e32 v32, v0
	v_mul_f32_e32 v0, 0xbfb8aa3b, v31
	v_exp_f32_e32 v0, v0
	s_nop 0
	v_add_f32_e32 v0, 1.0, v0
	v_rcp_f32_e32 v33, v0
	s_nop 0
	v_pk_mul_f32 v[30:31], v[32:33], v[30:31]
	s_nop 0
	v_pk_mul_f32 v[24:25], v[24:25], v[30:31]
	v_lshlrev_b32_e32 v30, 16, v29
	v_mul_f32_e32 v0, 0xbfb8aa3b, v30
	v_exp_f32_e32 v0, v0
	v_and_b32_e32 v31, 0xffff0000, v29
	v_cvt_pk_bf16_f32 v24, v24, v25
	v_add_f32_e32 v0, 1.0, v0
	v_rcp_f32_e32 v28, v0
; __device__ __forceinline__ float bf2f(short b) { return __uint_as_float(((unsigned)(unsigned short)b) << 16); }
; __device__ __forceinline__ u32x2 pack4(f32x4 a) { u32x2 w = {pk2(a[0], a[1]), pk2(a[2], a[3])}; return w; }
; __device__ __forceinline__ float fexp(float x) { return __builtin_amdgcn_exp2f(x * 1.4426950408889634f); }
; __device__ __forceinline__ void attn_phase(unsigned char* lds, const Params& p, int jl, const bf16_t* proj, bf16_t* mix, int blk, int G, int tid) {
;     ...
;                 for (int dt = 0; dt < 8; ++dt) { const bf16x4 gv = *(const bf16x4*)(gp + dt * 16); f32x4 ov;
; #pragma unroll
;                     for (int j = 0; j < 4; ++j) { const float gg = bf2f(gv[j]); ov[j] = o[qt][dt][j] * inv * (gg * __builtin_amdgcn_rcpf(1.f + fexp(-gg))); }
;                     *(u32x2*)(mp + dt * 16) = pack4(ov); }
	v_mul_f32_e32 v0, 0xbfb8aa3b, v31
	v_exp_f32_e32 v0, v0
	s_nop 0
	v_add_f32_e32 v0, 1.0, v0
	v_rcp_f32_e32 v29, v0
	s_nop 0
	v_pk_mul_f32 v[28:29], v[28:29], v[30:31]
	s_nop 0
	v_pk_mul_f32 v[26:27], v[26:27], v[28:29]
	s_nop 0
	v_cvt_pk_bf16_f32 v25, v26, v27
	global_store_dwordx2 v[2:3], v[24:25], off offset:64
	v_mov_b32_e32 v24, v236
	v_mov_b32_e32 v25, v237
	v_lshlrev_b32_e32 v26, 16, v24
	v_mul_f32_e32 v0, 0xbfb8aa3b, v26
	v_exp_f32_e32 v0, v0
	v_and_b32_e32 v27, 0xffff0000, v24
	v_add_f32_e32 v0, 1.0, v0
	v_rcp_f32_e32 v28, v0
	v_mul_f32_e32 v0, 0xbfb8aa3b, v27
	v_exp_f32_e32 v0, v0
	s_nop 0
	v_add_f32_e32 v0, 1.0, v0
	v_rcp_f32_e32 v29, v0
	s_nop 0
	v_pk_mul_f32 v[26:27], v[28:29], v[26:27]
	s_nop 0
	v_pk_mul_f32 v[20:21], v[20:21], v[26:27]
	v_lshlrev_b32_e32 v26, 16, v25
	v_mul_f32_e32 v0, 0xbfb8aa3b, v26
	v_exp_f32_e32 v0, v0
	v_and_b32_e32 v27, 0xffff0000, v25
	v_cvt_pk_bf16_f32 v20, v20, v21
	v_add_f32_e32 v0, 1.0, v0
	v_rcp_f32_e32 v24, v0
	v_mul_f32_e32 v0, 0xbfb8aa3b, v27
	v_exp_f32_e32 v0, v0
	s_nop 0
	v_add_f32_e32 v0, 1.0, v0
	v_rcp_f32_e32 v25, v0
	s_nop 0
	v_pk_mul_f32 v[24:25], v[24:25], v[26:27]
	s_nop 0
	v_pk_mul_f32 v[22:23], v[22:23], v[24:25]
	s_nop 0
	v_cvt_pk_bf16_f32 v21, v22, v23
	global_store_dwordx2 v[2:3], v[20:21], off offset:96
	v_mov_b32_e32 v20, v238
	v_mov_b32_e32 v21, v239
	v_lshlrev_b32_e32 v22, 16, v20
	v_mul_f32_e32 v0, 0xbfb8aa3b, v22
	v_exp_f32_e32 v0, v0
	v_and_b32_e32 v23, 0xffff0000, v20
	v_add_f32_e32 v0, 1.0, v0
	v_rcp_f32_e32 v24, v0
	v_mul_f32_e32 v0, 0xbfb8aa3b, v23
	v_exp_f32_e32 v0, v0
	s_nop 0
	v_add_f32_e32 v0, 1.0, v0
	v_rcp_f32_e32 v25, v0
	s_nop 0
	v_pk_mul_f32 v[22:23], v[24:25], v[22:23]
	s_nop 0
	v_pk_mul_f32 v[16:17], v[16:17], v[22:23]
	v_lshlrev_b32_e32 v22, 16, v21
	v_mul_f32_e32 v0, 0xbfb8aa3b, v22
	v_exp_f32_e32 v0, v0
	v_and_b32_e32 v23, 0xffff0000, v21
	v_cvt_pk_bf16_f32 v16, v16, v17
	v_add_f32_e32 v0, 1.0, v0
	v_rcp_f32_e32 v20, v0
	v_mul_f32_e32 v0, 0xbfb8aa3b, v23
	v_exp_f32_e32 v0, v0
	s_nop 0
	v_add_f32_e32 v0, 1.0, v0
	v_rcp_f32_e32 v21, v0
	s_nop 0
	v_pk_mul_f32 v[20:21], v[20:21], v[22:23]
	s_nop 0
	v_pk_mul_f32 v[18:19], v[18:19], v[20:21]
	s_nop 0
	v_cvt_pk_bf16_f32 v17, v18, v19
	global_store_dwordx2 v[2:3], v[16:17], off offset:128
	v_mov_b32_e32 v16, v240
	v_mov_b32_e32 v17, v241
	v_lshlrev_b32_e32 v18, 16, v16
	v_mul_f32_e32 v0, 0xbfb8aa3b, v18
	v_exp_f32_e32 v0, v0
	v_and_b32_e32 v19, 0xffff0000, v16
	v_add_f32_e32 v0, 1.0, v0
	v_rcp_f32_e32 v20, v0
	v_mul_f32_e32 v0, 0xbfb8aa3b, v19
	v_exp_f32_e32 v0, v0
	s_nop 0
	v_add_f32_e32 v0, 1.0, v0
	v_rcp_f32_e32 v21, v0
	s_nop 0
	v_pk_mul_f32 v[18:19], v[20:21], v[18:19]
	s_nop 0
	v_pk_mul_f32 v[12:13], v[12:13], v[18:19]
	v_lshlrev_b32_e32 v18, 16, v17
	v_mul_f32_e32 v0, 0xbfb8aa3b, v18
	v_exp_f32_e32 v0, v0
	v_and_b32_e32 v19, 0xffff0000, v17
	v_cvt_pk_bf16_f32 v12, v12, v13
	v_add_f32_e32 v0, 1.0, v0
	v_rcp_f32_e32 v16, v0
	v_mul_f32_e32 v0, 0xbfb8aa3b, v19
	v_exp_f32_e32 v0, v0
	s_nop 0
	v_add_f32_e32 v0, 1.0, v0
	v_rcp_f32_e32 v17, v0
	s_nop 0
	v_pk_mul_f32 v[16:17], v[16:17], v[18:19]
	s_nop 0
	v_pk_mul_f32 v[14:15], v[14:15], v[16:17]
	s_nop 0
	v_cvt_pk_bf16_f32 v13, v14, v15
	global_store_dwordx2 v[2:3], v[12:13], off offset:160
	v_mov_b32_e32 v12, v242
	v_mov_b32_e32 v13, v243
	v_lshlrev_b32_e32 v14, 16, v12
	v_mul_f32_e32 v0, 0xbfb8aa3b, v14
	v_exp_f32_e32 v0, v0
	v_and_b32_e32 v15, 0xffff0000, v12
	v_add_f32_e32 v0, 1.0, v0
	v_rcp_f32_e32 v16, v0
	v_mul_f32_e32 v0, 0xbfb8aa3b, v15
	v_exp_f32_e32 v0, v0
	s_nop 0
	v_add_f32_e32 v0, 1.0, v0
	v_rcp_f32_e32 v17, v0
	s_nop 0
	v_pk_mul_f32 v[14:15], v[16:17], v[14:15]
	s_nop 0
	v_pk_mul_f32 v[8:9], v[8:9], v[14:15]
	v_lshlrev_b32_e32 v14, 16, v13
	v_mul_f32_e32 v0, 0xbfb8aa3b, v14
	v_exp_f32_e32 v0, v0
	v_and_b32_e32 v15, 0xffff0000, v13
	v_cvt_pk_bf16_f32 v8, v8, v9
	v_add_f32_e32 v0, 1.0, v0
	v_rcp_f32_e32 v12, v0
	v_mul_f32_e32 v0, 0xbfb8aa3b, v15
	v_exp_f32_e32 v0, v0
	s_nop 0
	v_add_f32_e32 v0, 1.0, v0
	v_rcp_f32_e32 v13, v0
	s_nop 0
	v_pk_mul_f32 v[12:13], v[12:13], v[14:15]
	s_nop 0
	v_pk_mul_f32 v[10:11], v[10:11], v[12:13]
	s_nop 0
	v_cvt_pk_bf16_f32 v9, v10, v11
	global_store_dwordx2 v[2:3], v[8:9], off offset:192
	v_mov_b32_e32 v8, v244
	v_mov_b32_e32 v9, v245
	v_lshlrev_b32_e32 v10, 16, v8
	v_mul_f32_e32 v0, 0xbfb8aa3b, v10
	v_exp_f32_e32 v0, v0
	v_and_b32_e32 v11, 0xffff0000, v8
	v_add_f32_e32 v0, 1.0, v0
	v_rcp_f32_e32 v12, v0
	v_mul_f32_e32 v0, 0xbfb8aa3b, v11
	v_exp_f32_e32 v0, v0
	s_nop 0
	v_add_f32_e32 v0, 1.0, v0
	v_rcp_f32_e32 v13, v0
	s_nop 0
	v_pk_mul_f32 v[10:11], v[12:13], v[10:11]
	s_nop 0
	v_pk_mul_f32 v[4:5], v[4:5], v[10:11]
	v_lshlrev_b32_e32 v10, 16, v9
	v_mul_f32_e32 v0, 0xbfb8aa3b, v10
	v_exp_f32_e32 v0, v0
	v_and_b32_e32 v11, 0xffff0000, v9
	v_cvt_pk_bf16_f32 v4, v4, v5
	v_add_f32_e32 v0, 1.0, v0
	v_rcp_f32_e32 v8, v0
	v_mul_f32_e32 v0, 0xbfb8aa3b, v11
	v_exp_f32_e32 v0, v0
	s_nop 0
	v_add_f32_e32 v0, 1.0, v0
	v_rcp_f32_e32 v9, v0
	s_nop 0
	v_pk_mul_f32 v[8:9], v[8:9], v[10:11]
	s_nop 0
	v_pk_mul_f32 v[6:7], v[6:7], v[8:9]
	s_nop 0
	v_cvt_pk_bf16_f32 v5, v6, v7
	global_store_dwordx2 v[2:3], v[4:5], off offset:224
	s_branch .LBB0_132

; __device__ __forceinline__ float bf2f(short b) { return __uint_as_float(((unsigned)(unsigned short)b) << 16); }
; __device__ __forceinline__ float fexp(float x) { return __builtin_amdgcn_exp2f(x * 1.4426950408889634f); }
; __device__ __forceinline__ float flog(float x) { return __builtin_amdgcn_logf(x) * 0.6931471805599453f; }
; __device__ __forceinline__ void hgrn_a(unsigned char* lds, const Params& p, int jl, bf16_t* proj, bf16_t* mix, float* dbuf, bf16_t* scr, float* useg, float* dseg, int blk, int G, int tid) {
;     ...
;             float cum[16], kk[16], qs[16]; float run = 0.f;
; #pragma unroll
;             for (int i = 0; i < 16; ++i) { const int tok = tg * 16 + i; const float q = bf2f((short)RAWQ[tok * 136 + c]), z = bf2f((short)RAWZ[tok * 136 + c]);
;                 const float e = fexp(-fabsf(z)), r = __builtin_amdgcn_rcpf(1.f + e), er = e * r; const float sp = z >= 0.f ? r : er, sn = z >= 0.f ? er : r;
;                 float lf = flog(sp + lbe * sn), kv = oml * sn, qq = q * __builtin_amdgcn_rcpf(1.f + fexp(-q));
;                 if (nvalid < 64) { if (tok >= nvalid) { lf = 0.f; kv = 0.f; qq = 0.f; } }
;                 run += lf; cum[i] = run; kk[i] = kv; qs[i] = qq; }
;             TOT[tg * 128 + c] = run;
.LBB0_253:
	s_waitcnt lgkmcnt(0)
	s_barrier
	ds_read_u16 v220, v109
	ds_read_u16 v221, v109 offset:17408
	ds_read_u16 v222, v111
	ds_read_u16 v223, v111 offset:17408
	ds_read_u16 v224, v113
	ds_read_u16 v225, v113 offset:17408
	ds_read_u16 v226, v115
	ds_read_u16 v227, v115 offset:17408
	ds_read_u16 v228, v117
	ds_read_u16 v229, v117 offset:17408
	ds_read_u16 v230, v119
	ds_read_u16 v231, v119 offset:17408
	ds_read_u16 v232, v121
	ds_read_u16 v233, v121 offset:17408
	s_mov_b32 s28, 0x3f317218
	v_readlane_b32 s38, v255, 30
	v_readlane_b32 s39, v255, 31
	s_waitcnt lgkmcnt(12)
	v_lshlrev_b32_e32 v58, 16, v220
	v_lshlrev_b32_e32 v59, 16, v221
	v_mul_f32_e64 v60, |v59|, s33
	v_exp_f32_e32 v60, v60
	v_cmp_le_f32_e32 vcc, 0, v59
	v_mov_b32_e32 v127, v1
	v_add_f32_e32 v61, 1.0, v60
	v_rcp_f32_e32 v61, v61
	s_nop 0
	v_mul_f32_e32 v60, v60, v61
	v_cndmask_b32_e32 v59, v60, v61, vcc
	v_cndmask_b32_e32 v60, v61, v60, vcc
	v_mul_f32_e32 v61, 0xbfb8aa3b, v58
	v_exp_f32_e32 v61, v61
	v_fmac_f32_e32 v59, v168, v60
	v_log_f32_e32 v59, v59
	v_mul_f32_e32 v60, v169, v60
	v_add_f32_e32 v61, 1.0, v61
	v_rcp_f32_e32 v61, v61
	v_cndmask_b32_e64 v65, 0, v60, s[76:77]
	v_mul_f32_e32 v58, v61, v58
	v_cndmask_b32_e64 v64, 0, v58, s[76:77]
	v_fma_f32 v58, v59, s28, 0
	v_cndmask_b32_e64 v66, 0, v58, s[76:77]
	ds_read_u16 v234, v123
	ds_read_u16 v235, v123 offset:17408
	s_waitcnt lgkmcnt(12)
	v_lshlrev_b32_e32 v58, 16, v222
	v_lshlrev_b32_e32 v59, 16, v223
	v_mul_f32_e64 v60, |v59|, s33
	v_exp_f32_e32 v60, v60
	v_cmp_le_f32_e32 vcc, 0, v59
	v_add_f32_e32 v61, 1.0, v60
	v_rcp_f32_e32 v61, v61
	s_nop 0
	v_mul_f32_e32 v60, v60, v61
	v_cndmask_b32_e32 v59, v60, v61, vcc
	v_cndmask_b32_e32 v60, v61, v60, vcc
	v_mul_f32_e32 v61, 0xbfb8aa3b, v58
	v_exp_f32_e32 v61, v61
	v_fmac_f32_e32 v59, v168, v60
	v_log_f32_e32 v59, v59
	v_mul_f32_e32 v60, v169, v60
	v_add_f32_e32 v61, 1.0, v61
	v_rcp_f32_e32 v61, v61
	v_mul_f32_e32 v59, 0x3f317218, v59
	v_cndmask_b32_e64 v68, 0, v60, s[78:79]
	v_mul_f32_e32 v58, v61, v58
	v_cndmask_b32_e64 v67, 0, v58, s[78:79]
	v_cndmask_b32_e64 v58, 0, v59, s[78:79]
	v_add_f32_e32 v69, v66, v58
	ds_read_u16 v236, v125
	ds_read_u16 v237, v125 offset:17408
	s_waitcnt lgkmcnt(12)
	v_lshlrev_b32_e32 v58, 16, v224
	v_lshlrev_b32_e32 v59, 16, v225
	v_mul_f32_e64 v60, |v59|, s33
	v_exp_f32_e32 v60, v60
	v_cmp_le_f32_e32 vcc, 0, v59
	v_add_f32_e32 v61, 1.0, v60
	v_rcp_f32_e32 v61, v61
	s_nop 0
	v_mul_f32_e32 v60, v60, v61
	v_cndmask_b32_e32 v59, v60, v61, vcc
	v_cndmask_b32_e32 v60, v61, v60, vcc
	v_mul_f32_e32 v61, 0xbfb8aa3b, v58
	v_exp_f32_e32 v61, v61
	v_fmac_f32_e32 v59, v168, v60
	v_log_f32_e32 v59, v59
	v_mul_f32_e32 v60, v169, v60
	v_add_f32_e32 v61, 1.0, v61
	v_rcp_f32_e32 v61, v61
	v_mul_f32_e32 v59, 0x3f317218, v59
	v_cndmask_b32_e64 v71, 0, v60, s[80:81]
	v_mul_f32_e32 v58, v61, v58
	v_cndmask_b32_e64 v70, 0, v58, s[80:81]
	v_cndmask_b32_e64 v58, 0, v59, s[80:81]
	v_add_f32_e32 v72, v69, v58
	ds_read_u16 v238, v142
	ds_read_u16 v239, v142 offset:17408
	s_waitcnt lgkmcnt(12)
	v_lshlrev_b32_e32 v58, 16, v226
	v_lshlrev_b32_e32 v59, 16, v227
	v_mul_f32_e64 v60, |v59|, s33
	v_exp_f32_e32 v60, v60
	v_cmp_le_f32_e32 vcc, 0, v59
	v_add_f32_e32 v61, 1.0, v60
	v_rcp_f32_e32 v61, v61
	s_nop 0
	v_mul_f32_e32 v60, v60, v61
	v_cndmask_b32_e32 v59, v60, v61, vcc
	v_cndmask_b32_e32 v60, v61, v60, vcc
	v_mul_f32_e32 v61, 0xbfb8aa3b, v58
	v_exp_f32_e32 v61, v61
	v_fmac_f32_e32 v59, v168, v60
	v_log_f32_e32 v59, v59
	v_mul_f32_e32 v60, v169, v60
	v_add_f32_e32 v61, 1.0, v61
	v_rcp_f32_e32 v61, v61
	v_mul_f32_e32 v59, 0x3f317218, v59
	v_cndmask_b32_e64 v129, 0, v60, s[82:83]
	v_mul_f32_e32 v58, v61, v58
	v_cndmask_b32_e64 v73, 0, v58, s[82:83]
	v_cndmask_b32_e64 v58, 0, v59, s[82:83]
	v_add_f32_e32 v135, v72, v58
	ds_read_u16 v240, v143
	ds_read_u16 v241, v143 offset:17408
	s_waitcnt lgkmcnt(12)
	v_lshlrev_b32_e32 v58, 16, v228
	v_lshlrev_b32_e32 v59, 16, v229
	v_mul_f32_e64 v60, |v59|, s33
	v_exp_f32_e32 v60, v60
	v_cmp_le_f32_e32 vcc, 0, v59
	v_add_f32_e32 v61, 1.0, v60
	v_rcp_f32_e32 v61, v61
	s_nop 0
	v_mul_f32_e32 v60, v60, v61
	v_cndmask_b32_e32 v59, v60, v61, vcc
	v_cndmask_b32_e32 v60, v61, v60, vcc
	v_mul_f32_e32 v61, 0xbfb8aa3b, v58
	v_exp_f32_e32 v61, v61
	v_fmac_f32_e32 v59, v168, v60
	v_log_f32_e32 v59, v59
	v_mul_f32_e32 v60, v169, v60
	v_add_f32_e32 v61, 1.0, v61
	v_rcp_f32_e32 v61, v61
	v_mul_f32_e32 v59, 0x3f317218, v59
	v_cndmask_b32_e64 v133, 0, v60, s[84:85]
	v_mul_f32_e32 v58, v61, v58
	v_cndmask_b32_e64 v131, 0, v58, s[84:85]
	v_cndmask_b32_e64 v58, 0, v59, s[84:85]
	v_add_f32_e32 v137, v135, v58
	ds_read_u16 v242, v144
	ds_read_u16 v243, v144 offset:17408
	s_waitcnt lgkmcnt(12)
	v_lshlrev_b32_e32 v58, 16, v230
	v_lshlrev_b32_e32 v59, 16, v231
	v_mul_f32_e64 v60, |v59|, s33
	v_exp_f32_e32 v60, v60
	v_cmp_le_f32_e32 vcc, 0, v59
	v_add_f32_e32 v61, 1.0, v60
	v_rcp_f32_e32 v61, v61
	s_nop 0
	v_mul_f32_e32 v60, v60, v61
	v_cndmask_b32_e32 v59, v60, v61, vcc
	v_cndmask_b32_e32 v60, v61, v60, vcc
	v_mul_f32_e32 v61, 0xbfb8aa3b, v58
	v_exp_f32_e32 v61, v61
	v_fmac_f32_e32 v59, v168, v60
	v_log_f32_e32 v59, v59
	v_mul_f32_e32 v60, v169, v60
	v_add_f32_e32 v61, 1.0, v61
	v_rcp_f32_e32 v61, v61
	v_mul_f32_e32 v59, 0x3f317218, v59
	v_cndmask_b32_e64 v171, 0, v60, s[86:87]
	v_mul_f32_e32 v58, v61, v58
	v_cndmask_b32_e64 v170, 0, v58, s[86:87]
	v_cndmask_b32_e64 v58, 0, v59, s[86:87]
	v_add_f32_e32 v172, v137, v58
	ds_read_u16 v244, v145
	ds_read_u16 v245, v145 offset:17408
	s_waitcnt lgkmcnt(12)
; __device__ __forceinline__ float bf2f(short b) { return __uint_as_float(((unsigned)(unsigned short)b) << 16); }
; __device__ __forceinline__ float fexp(float x) { return __builtin_amdgcn_exp2f(x * 1.4426950408889634f); }
; __device__ __forceinline__ float flog(float x) { return __builtin_amdgcn_logf(x) * 0.6931471805599453f; }
; __device__ __forceinline__ void hgrn_a(unsigned char* lds, const Params& p, int jl, bf16_t* proj, bf16_t* mix, float* dbuf, bf16_t* scr, float* useg, float* dseg, int blk, int G, int tid) {
;     ...
; #pragma unroll
;             for (int i = 0; i < 16; ++i) { const int tok = tg * 16 + i; const float q = bf2f((short)RAWQ[tok * 136 + c]), z = bf2f((short)RAWZ[tok * 136 + c]);
;                 const float e = fexp(-fabsf(z)), r = __builtin_amdgcn_rcpf(1.f + e), er = e * r; const float sp = z >= 0.f ? r : er, sn = z >= 0.f ? er : r;
;                 float lf = flog(sp + lbe * sn), kv = oml * sn, qq = q * __builtin_amdgcn_rcpf(1.f + fexp(-q));
;                 if (nvalid < 64) { if (tok >= nvalid) { lf = 0.f; kv = 0.f; qq = 0.f; } }
;                 run += lf; cum[i] = run; kk[i] = kv; qs[i] = qq; }
	v_lshlrev_b32_e32 v58, 16, v232
	v_lshlrev_b32_e32 v59, 16, v233
	v_mul_f32_e64 v60, |v59|, s33
	v_exp_f32_e32 v60, v60
	v_cmp_le_f32_e32 vcc, 0, v59
	v_add_f32_e32 v61, 1.0, v60
	v_rcp_f32_e32 v61, v61
	s_nop 0
	v_mul_f32_e32 v60, v60, v61
	v_cndmask_b32_e32 v59, v60, v61, vcc
	v_cndmask_b32_e32 v60, v61, v60, vcc
	v_mul_f32_e32 v61, 0xbfb8aa3b, v58
	v_exp_f32_e32 v61, v61
	v_fmac_f32_e32 v59, v168, v60
	v_log_f32_e32 v59, v59
	v_mul_f32_e32 v60, v169, v60
	v_add_f32_e32 v61, 1.0, v61
	v_rcp_f32_e32 v61, v61
	v_mul_f32_e32 v59, 0x3f317218, v59
	v_cndmask_b32_e64 v174, 0, v60, s[88:89]
	v_mul_f32_e32 v58, v61, v58
	v_cndmask_b32_e64 v173, 0, v58, s[88:89]
	v_cndmask_b32_e64 v58, 0, v59, s[88:89]
	v_add_f32_e32 v175, v172, v58
	ds_read_u16 v246, v146
	ds_read_u16 v247, v146 offset:17408
	s_waitcnt lgkmcnt(12)
	v_lshlrev_b32_e32 v58, 16, v234
	v_lshlrev_b32_e32 v59, 16, v235
	v_mul_f32_e64 v60, |v59|, s33
	v_exp_f32_e32 v60, v60
	v_cmp_le_f32_e32 vcc, 0, v59
	v_add_f32_e32 v61, 1.0, v60
	v_rcp_f32_e32 v61, v61
	s_nop 0
	v_mul_f32_e32 v60, v60, v61
	v_cndmask_b32_e32 v59, v60, v61, vcc
	v_cndmask_b32_e32 v60, v61, v60, vcc
	v_mul_f32_e32 v61, 0xbfb8aa3b, v58
	v_exp_f32_e32 v61, v61
	v_fmac_f32_e32 v59, v168, v60
	v_log_f32_e32 v59, v59
	v_mul_f32_e32 v60, v169, v60
	v_add_f32_e32 v61, 1.0, v61
	v_rcp_f32_e32 v61, v61
	v_mul_f32_e32 v59, 0x3f317218, v59
	v_cndmask_b32_e64 v177, 0, v60, s[90:91]
	v_mul_f32_e32 v58, v61, v58
	v_cndmask_b32_e64 v176, 0, v58, s[90:91]
	v_cndmask_b32_e64 v58, 0, v59, s[90:91]
	v_add_f32_e32 v180, v175, v58
	ds_read_u16 v248, v147
	ds_read_u16 v249, v147 offset:17408
	s_waitcnt lgkmcnt(12)
	v_lshlrev_b32_e32 v58, 16, v236
	v_lshlrev_b32_e32 v59, 16, v237
	v_mul_f32_e64 v60, |v59|, s33
	v_exp_f32_e32 v60, v60
	v_cmp_le_f32_e32 vcc, 0, v59
	v_add_f32_e32 v61, 1.0, v60
	v_rcp_f32_e32 v61, v61
	s_nop 0
	v_mul_f32_e32 v60, v60, v61
	v_cndmask_b32_e32 v59, v60, v61, vcc
	v_cndmask_b32_e32 v60, v61, v60, vcc
	v_mul_f32_e32 v61, 0xbfb8aa3b, v58
	v_exp_f32_e32 v61, v61
	v_fmac_f32_e32 v59, v168, v60
	v_log_f32_e32 v59, v59
	v_mul_f32_e32 v60, v169, v60
	v_add_f32_e32 v61, 1.0, v61
	v_rcp_f32_e32 v61, v61
	v_mul_f32_e32 v59, 0x3f317218, v59
	v_cndmask_b32_e64 v179, 0, v60, s[92:93]
	v_mul_f32_e32 v58, v61, v58
	v_cndmask_b32_e64 v178, 0, v58, s[92:93]
	v_cndmask_b32_e64 v58, 0, v59, s[92:93]
	v_add_f32_e32 v181, v180, v58
	ds_read_u16 v250, v158
	ds_read_u16 v251, v158 offset:17408
	s_waitcnt lgkmcnt(12)
	v_lshlrev_b32_e32 v58, 16, v238
	v_lshlrev_b32_e32 v59, 16, v239
	v_mul_f32_e64 v60, |v59|, s33
	v_exp_f32_e32 v60, v60
	v_cmp_le_f32_e32 vcc, 0, v59
	v_add_f32_e32 v61, 1.0, v60
	v_rcp_f32_e32 v61, v61
	s_nop 0
	v_mul_f32_e32 v60, v60, v61
	v_cndmask_b32_e32 v59, v60, v61, vcc
	v_cndmask_b32_e32 v60, v61, v60, vcc
	v_mul_f32_e32 v61, 0xbfb8aa3b, v58
	v_exp_f32_e32 v61, v61
	v_fmac_f32_e32 v59, v168, v60
	v_log_f32_e32 v59, v59
	v_mul_f32_e32 v60, v169, v60
	v_add_f32_e32 v61, 1.0, v61
	v_rcp_f32_e32 v61, v61
	v_mul_f32_e32 v59, 0x3f317218, v59
	v_cndmask_b32_e64 v183, 0, v60, s[94:95]
	v_mul_f32_e32 v58, v61, v58
	v_cndmask_b32_e64 v182, 0, v58, s[94:95]
	v_cndmask_b32_e64 v58, 0, v59, s[94:95]
	v_add_f32_e32 v184, v181, v58
	s_waitcnt lgkmcnt(10)
	v_lshlrev_b32_e32 v58, 16, v240
	v_lshlrev_b32_e32 v59, 16, v241
	v_mul_f32_e64 v60, |v59|, s33
	v_exp_f32_e32 v60, v60
	v_cmp_le_f32_e32 vcc, 0, v59
	v_add_f32_e32 v61, 1.0, v60
	v_rcp_f32_e32 v61, v61
	s_nop 0
	v_mul_f32_e32 v60, v60, v61
	v_cndmask_b32_e32 v59, v60, v61, vcc
	v_cndmask_b32_e32 v60, v61, v60, vcc
	v_mul_f32_e32 v61, 0xbfb8aa3b, v58
	v_exp_f32_e32 v61, v61
	v_fmac_f32_e32 v59, v168, v60
	v_log_f32_e32 v59, v59
	v_mul_f32_e32 v60, v169, v60
	v_add_f32_e32 v61, 1.0, v61
	v_rcp_f32_e32 v61, v61
	v_mul_f32_e32 v59, 0x3f317218, v59
	v_cndmask_b32_e64 v186, 0, v60, s[96:97]
	v_mul_f32_e32 v58, v61, v58
	v_cndmask_b32_e64 v185, 0, v58, s[96:97]
	v_cndmask_b32_e64 v58, 0, v59, s[96:97]
	v_add_f32_e32 v187, v184, v58
	s_waitcnt lgkmcnt(8)
	v_lshlrev_b32_e32 v58, 16, v242
	v_lshlrev_b32_e32 v59, 16, v243
	v_mul_f32_e64 v60, |v59|, s33
	v_exp_f32_e32 v60, v60
	v_cmp_le_f32_e32 vcc, 0, v59
	v_add_f32_e32 v61, 1.0, v60
	v_rcp_f32_e32 v61, v61
	s_nop 0
	v_mul_f32_e32 v60, v60, v61
	v_cndmask_b32_e32 v59, v60, v61, vcc
	v_cndmask_b32_e32 v60, v61, v60, vcc
	v_mul_f32_e32 v61, 0xbfb8aa3b, v58
	v_exp_f32_e32 v61, v61
	v_fmac_f32_e32 v59, v168, v60
	v_log_f32_e32 v59, v59
	v_mul_f32_e32 v60, v169, v60
	v_add_f32_e32 v61, 1.0, v61
	v_rcp_f32_e32 v61, v61
	v_mul_f32_e32 v59, 0x3f317218, v59
	v_cndmask_b32_e64 v189, 0, v60, s[98:99]
	v_mul_f32_e32 v58, v61, v58
	v_cndmask_b32_e64 v188, 0, v58, s[98:99]
	v_cndmask_b32_e64 v58, 0, v59, s[98:99]
	v_add_f32_e32 v192, v187, v58
	s_waitcnt lgkmcnt(6)
	v_lshlrev_b32_e32 v58, 16, v244
	v_lshlrev_b32_e32 v59, 16, v245
	v_mul_f32_e64 v60, |v59|, s33
	v_exp_f32_e32 v60, v60
	v_cmp_le_f32_e32 vcc, 0, v59
	v_add_f32_e32 v61, 1.0, v60
	v_rcp_f32_e32 v61, v61
	s_nop 0
	v_mul_f32_e32 v60, v60, v61
	v_cndmask_b32_e32 v59, v60, v61, vcc
	v_cndmask_b32_e32 v60, v61, v60, vcc
	v_mul_f32_e32 v61, 0xbfb8aa3b, v58
	v_exp_f32_e32 v61, v61
	v_fmac_f32_e32 v59, v168, v60
	v_log_f32_e32 v59, v59
	v_mul_f32_e32 v60, v169, v60
	v_add_f32_e32 v61, 1.0, v61
	v_rcp_f32_e32 v61, v61
	v_mul_f32_e32 v59, 0x3f317218, v59
	v_cndmask_b32_e64 v191, 0, v60, s[12:13]
	v_mul_f32_e32 v58, v61, v58
	v_cndmask_b32_e64 v190, 0, v58, s[12:13]
	v_cndmask_b32_e64 v58, 0, v59, s[12:13]
	v_add_f32_e32 v193, v192, v58
	s_waitcnt lgkmcnt(4)
; __device__ __forceinline__ bf16_t f2bf(float f) { return (bf16_t)(pk2(f, 0.f) & 0xffffu); }
; __device__ __forceinline__ float bf2f(short b) { return __uint_as_float(((unsigned)(unsigned short)b) << 16); }
; __device__ __forceinline__ float fexp(float x) { return __builtin_amdgcn_exp2f(x * 1.4426950408889634f); }
; __device__ __forceinline__ float flog(float x) { return __builtin_amdgcn_logf(x) * 0.6931471805599453f; }
; __device__ __forceinline__ void hgrn_a(unsigned char* lds, const Params& p, int jl, bf16_t* proj, bf16_t* mix, float* dbuf, bf16_t* scr, float* useg, float* dseg, int blk, int G, int tid) {
;     ...
;             for (int i = 0; i < 16; ++i) { const int tok = tg * 16 + i; const float q = bf2f((short)RAWQ[tok * 136 + c]), z = bf2f((short)RAWZ[tok * 136 + c]);
;                 const float e = fexp(-fabsf(z)), r = __builtin_amdgcn_rcpf(1.f + e), er = e * r; const float sp = z >= 0.f ? r : er, sn = z >= 0.f ? er : r;
;                 float lf = flog(sp + lbe * sn), kv = oml * sn, qq = q * __builtin_amdgcn_rcpf(1.f + fexp(-q));
;                 if (nvalid < 64) { if (tok >= nvalid) { lf = 0.f; kv = 0.f; qq = 0.f; } }
;                 run += lf; cum[i] = run; kk[i] = kv; qs[i] = qq; }
;             TOT[tg * 128 + c] = run;
;             __syncthreads();
;             const float t0 = TOT[c], t1 = TOT[128 + c], t2 = TOT[256 + c], t3 = TOT[384 + c];
;             const float off = (tg > 0 ? t0 : 0.f) + (tg > 1 ? t1 : 0.f) + (tg > 2 ? t2 : 0.f), bend = (t0 + t1) + (t2 + t3), bref = t0 + t1;
;             const float eref = fexp(bref), eend = fexp(bend - bref);
;             float kh[16];
; #pragma unroll
;             for (int i = 0; i < 16; ++i) { const int tok = tg * 16 + i; const float bt = off + cum[i];
;                 const float e1 = fexp(bt - bref), e2 = fexp(bref - bt);
;                 const float qt = qs[i] * e1, kt2 = kk[i] * e2, qh = qt * eref; kh[i] = kt2 * eend;
;                 QT[tok * 136 + c] = f2bf(qt); KTL[tok * 136 + c] = f2bf(kt2); qd[(size_t)tok * dstride + c] = f2bf(qh); }
	v_lshlrev_b32_e32 v58, 16, v246
	v_lshlrev_b32_e32 v59, 16, v247
	v_mul_f32_e64 v60, |v59|, s33
	v_exp_f32_e32 v60, v60
	v_cmp_le_f32_e32 vcc, 0, v59
	v_add_f32_e32 v61, 1.0, v60
	v_rcp_f32_e32 v61, v61
	s_nop 0
	v_mul_f32_e32 v60, v60, v61
	v_cndmask_b32_e32 v59, v60, v61, vcc
	v_cndmask_b32_e32 v60, v61, v60, vcc
	v_mul_f32_e32 v61, 0xbfb8aa3b, v58
	v_exp_f32_e32 v61, v61
	v_fmac_f32_e32 v59, v168, v60
	v_log_f32_e32 v59, v59
	v_mul_f32_e32 v60, v169, v60
	v_add_f32_e32 v61, 1.0, v61
	v_rcp_f32_e32 v61, v61
	v_mul_f32_e32 v59, 0x3f317218, v59
	v_cndmask_b32_e64 v195, 0, v60, s[4:5]
	v_mul_f32_e32 v58, v61, v58
	v_cndmask_b32_e64 v194, 0, v58, s[4:5]
	v_cndmask_b32_e64 v58, 0, v59, s[4:5]
	v_add_f32_e32 v196, v193, v58
	s_waitcnt lgkmcnt(2)
	v_lshlrev_b32_e32 v58, 16, v248
	v_lshlrev_b32_e32 v59, 16, v249
	v_mul_f32_e64 v60, |v59|, s33
	v_exp_f32_e32 v60, v60
	v_cmp_le_f32_e32 vcc, 0, v59
	v_add_f32_e32 v61, 1.0, v60
	v_rcp_f32_e32 v61, v61
	s_nop 0
	v_mul_f32_e32 v60, v60, v61
	v_cndmask_b32_e32 v59, v60, v61, vcc
	v_cndmask_b32_e32 v60, v61, v60, vcc
	v_mul_f32_e32 v61, 0xbfb8aa3b, v58
	v_exp_f32_e32 v61, v61
	v_fmac_f32_e32 v59, v168, v60
	v_log_f32_e32 v59, v59
	v_mul_f32_e32 v60, v169, v60
	v_add_f32_e32 v61, 1.0, v61
	v_rcp_f32_e32 v61, v61
	v_mul_f32_e32 v59, 0x3f317218, v59
	v_cndmask_b32_e64 v198, 0, v60, s[6:7]
	v_mul_f32_e32 v58, v61, v58
	v_cndmask_b32_e64 v197, 0, v58, s[6:7]
	v_cndmask_b32_e64 v58, 0, v59, s[6:7]
	v_add_f32_e32 v199, v196, v58
	s_waitcnt lgkmcnt(0)
	v_lshlrev_b32_e32 v58, 16, v250
	v_lshlrev_b32_e32 v59, 16, v251
	v_mul_f32_e64 v60, |v59|, s33
	v_exp_f32_e32 v60, v60
	v_cmp_le_f32_e32 vcc, 0, v59
	v_add_f32_e32 v61, 1.0, v60
	v_rcp_f32_e32 v61, v61
	s_nop 0
	v_mul_f32_e32 v60, v60, v61
	v_cndmask_b32_e32 v59, v60, v61, vcc
	v_cndmask_b32_e32 v60, v61, v60, vcc
	v_mul_f32_e32 v61, 0xbfb8aa3b, v58
	v_exp_f32_e32 v61, v61
	v_fmac_f32_e32 v59, v168, v60
	v_log_f32_e32 v59, v59
	v_mul_f32_e32 v60, v169, v60
	v_add_f32_e32 v61, 1.0, v61
	v_rcp_f32_e32 v61, v61
	v_mul_f32_e32 v59, 0x3f317218, v59
	v_cndmask_b32_e64 v201, 0, v60, s[8:9]
	v_mul_f32_e32 v58, v61, v58
	v_cndmask_b32_e64 v200, 0, v58, s[8:9]
	v_cndmask_b32_e64 v58, 0, v59, s[8:9]
	v_add_f32_e32 v202, v199, v58
	ds_write_b32 v87, v202
	s_waitcnt lgkmcnt(0)
	s_barrier
	ds_read2st64_b32 v[58:59], v95 offset1:2
	ds_read2st64_b32 v[60:61], v95 offset0:4 offset1:6
	s_waitcnt lgkmcnt(1)
	v_cndmask_b32_e64 v62, 0, v58, s[38:39]
	v_readlane_b32 s38, v255, 32
	v_readlane_b32 s39, v255, 33
	s_nop 1
	v_cndmask_b32_e64 v63, 0, v59, s[38:39]
	v_readlane_b32 s38, v255, 34
	v_readlane_b32 s39, v255, 35
	v_add_f32_e32 v62, v62, v63
	s_waitcnt lgkmcnt(0)
	v_cndmask_b32_e64 v63, 0, v60, s[38:39]
	v_add_f32_e32 v203, v62, v63
	v_mov_b32_e32 v62, v58
	v_mov_b32_e32 v63, v60
	v_mov_b32_e32 v60, v59
	v_pk_add_f32 v[62:63], v[62:63], v[60:61]
	v_add_f32_e32 v66, v66, v203
	v_pk_add_f32 v[58:59], v[62:63], v[62:63] op_sel:[0,1] op_sel_hi:[1,0]
	s_nop 0
	v_sub_f32_e32 v60, v58, v62
	v_mul_f32_e32 v60, 0x3fb8aa3b, v60
	v_exp_f32_e32 v63, v60
	v_lshl_add_u64 v[60:61], s[34:35], 0, v[126:127]
	v_sub_f32_e32 v127, v66, v62
	v_sub_f32_e32 v66, v62, v66
	v_mul_f32_e32 v127, 0x3fb8aa3b, v127
	v_mul_f32_e32 v66, 0x3fb8aa3b, v66
	v_mul_f32_e32 v59, 0x3fb8aa3b, v62
	v_exp_f32_e32 v127, v127
	v_exp_f32_e32 v66, v66
	v_exp_f32_e32 v59, v59
	v_mad_i64_i32 v[152:153], s[34:35], s30, v90, 0
	v_mul_f32_e32 v127, v64, v127
	v_mul_f32_e32 v65, v65, v66
	v_mul_f32_e32 v66, v59, v127
	v_mul_f32_e32 v64, v63, v65
	v_cvt_pk_bf16_f32 v65, v65, s0
	ds_write_b16 v109, v65 offset:52224
	v_cvt_pk_bf16_f32 v65, v66, s0
	v_lshl_add_u64 v[152:153], v[152:153], 1, v[60:61]
	global_store_short v[152:153], v65, off
	v_add_f32_e32 v65, v69, v203
	v_sub_f32_e32 v66, v65, v62
	v_mul_f32_e32 v66, 0x3fb8aa3b, v66
	v_sub_f32_e32 v65, v62, v65
	v_exp_f32_e32 v66, v66
	v_mul_f32_e32 v65, 0x3fb8aa3b, v65
	v_exp_f32_e32 v65, v65
	v_cvt_pk_bf16_f32 v127, v127, s0
	v_mul_f32_e32 v66, v67, v66
	ds_write_b16 v109, v127 offset:34816
	v_mul_f32_e32 v67, v68, v65
	v_mul_f32_e32 v68, v59, v66
	v_cvt_pk_bf16_f32 v66, v66, s0
	ds_write_b16 v111, v66 offset:34816
	v_cvt_pk_bf16_f32 v66, v67, s0
	v_mul_f32_e32 v65, v63, v67
	ds_write_b16 v111, v66 offset:52224
	v_mad_i64_i32 v[66:67], s[34:35], s30, v94, 0
	v_cvt_pk_bf16_f32 v68, v68, s0
	v_lshl_add_u64 v[66:67], v[66:67], 1, v[60:61]
	global_store_short v[66:67], v68, off
	v_add_f32_e32 v66, v72, v203
	v_sub_f32_e32 v67, v66, v62
	v_sub_f32_e32 v66, v62, v66
	v_mul_f32_e32 v67, 0x3fb8aa3b, v67
	v_mul_f32_e32 v66, 0x3fb8aa3b, v66
	v_exp_f32_e32 v67, v67
	v_exp_f32_e32 v66, v66
	v_mul_f32_e32 v67, v70, v67
	v_mul_f32_e32 v66, v71, v66
	v_mul_f32_e32 v68, v59, v67
	v_mul_f32_e32 v69, v63, v66
	v_cvt_pk_bf16_f32 v67, v67, s0
	v_cvt_pk_bf16_f32 v66, v66, s0
	ds_write_b16 v113, v67 offset:34816
	ds_write_b16 v113, v66 offset:52224
	v_mad_i64_i32 v[66:67], s[34:35], s30, v96, 0
	v_cvt_pk_bf16_f32 v68, v68, s0
	v_lshl_add_u64 v[66:67], v[66:67], 1, v[60:61]
	global_store_short v[66:67], v68, off
	v_add_f32_e32 v66, v135, v203
	v_sub_f32_e32 v67, v66, v62
	v_sub_f32_e32 v66, v62, v66
	v_mul_f32_e32 v67, 0x3fb8aa3b, v67
	v_mul_f32_e32 v66, 0x3fb8aa3b, v66
	v_exp_f32_e32 v67, v67
	v_exp_f32_e32 v66, v66
	v_mul_f32_e32 v67, v73, v67
	v_mul_f32_e32 v66, v129, v66
	v_mul_f32_e32 v68, v59, v67
	v_mul_f32_e32 v70, v63, v66
	v_cvt_pk_bf16_f32 v67, v67, s0
	v_cvt_pk_bf16_f32 v66, v66, s0
	ds_write_b16 v115, v67 offset:34816
	ds_write_b16 v115, v66 offset:52224
	v_mad_i64_i32 v[66:67], s[34:35], s30, v98, 0
	v_cvt_pk_bf16_f32 v68, v68, s0
	v_lshl_add_u64 v[66:67], v[66:67], 1, v[60:61]
; __device__ __forceinline__ bf16_t f2bf(float f) { return (bf16_t)(pk2(f, 0.f) & 0xffffu); }
; __device__ __forceinline__ float fexp(float x) { return __builtin_amdgcn_exp2f(x * 1.4426950408889634f); }
; __device__ __forceinline__ void hgrn_a(unsigned char* lds, const Params& p, int jl, bf16_t* proj, bf16_t* mix, float* dbuf, bf16_t* scr, float* useg, float* dseg, int blk, int G, int tid) {
;     ...
;             for (int i = 0; i < 16; ++i) { const int tok = tg * 16 + i; const float bt = off + cum[i];
;                 const float e1 = fexp(bt - bref), e2 = fexp(bref - bt);
;                 const float qt = qs[i] * e1, kt2 = kk[i] * e2, qh = qt * eref; kh[i] = kt2 * eend;
;                 QT[tok * 136 + c] = f2bf(qt); KTL[tok * 136 + c] = f2bf(kt2); qd[(size_t)tok * dstride + c] = f2bf(qh); }
	global_store_short v[66:67], v68, off
	v_add_f32_e32 v66, v137, v203
	v_sub_f32_e32 v67, v66, v62
	v_sub_f32_e32 v66, v62, v66
	v_mul_f32_e32 v67, 0x3fb8aa3b, v67
	v_mul_f32_e32 v66, 0x3fb8aa3b, v66
	v_exp_f32_e32 v67, v67
	v_exp_f32_e32 v66, v66
	v_mul_f32_e32 v67, v131, v67
	v_mul_f32_e32 v66, v133, v66
	v_mul_f32_e32 v68, v59, v67
	v_mul_f32_e32 v71, v63, v66
	v_cvt_pk_bf16_f32 v67, v67, s0
	v_cvt_pk_bf16_f32 v66, v66, s0
	ds_write_b16 v117, v67 offset:34816
	ds_write_b16 v117, v66 offset:52224
	v_mad_i64_i32 v[66:67], s[34:35], s30, v100, 0
	v_cvt_pk_bf16_f32 v68, v68, s0
	v_lshl_add_u64 v[66:67], v[66:67], 1, v[60:61]
	global_store_short v[66:67], v68, off
	v_add_f32_e32 v66, v172, v203
	v_sub_f32_e32 v67, v66, v62
	v_sub_f32_e32 v66, v62, v66
	v_mul_f32_e32 v67, 0x3fb8aa3b, v67
	v_mul_f32_e32 v66, 0x3fb8aa3b, v66
	v_exp_f32_e32 v67, v67
	v_exp_f32_e32 v66, v66
	v_mul_f32_e32 v67, v170, v67
	v_mul_f32_e32 v66, v171, v66
	v_mul_f32_e32 v68, v59, v67
	v_mul_f32_e32 v72, v63, v66
	v_cvt_pk_bf16_f32 v67, v67, s0
	v_cvt_pk_bf16_f32 v66, v66, s0
	ds_write_b16 v119, v67 offset:34816
	ds_write_b16 v119, v66 offset:52224
	v_mad_i64_i32 v[66:67], s[34:35], s30, v102, 0
	v_cvt_pk_bf16_f32 v68, v68, s0
	v_lshl_add_u64 v[66:67], v[66:67], 1, v[60:61]
	global_store_short v[66:67], v68, off
	v_add_f32_e32 v66, v175, v203
	v_sub_f32_e32 v67, v66, v62
	v_sub_f32_e32 v66, v62, v66
	v_mul_f32_e32 v67, 0x3fb8aa3b, v67
	v_mul_f32_e32 v66, 0x3fb8aa3b, v66
	v_exp_f32_e32 v67, v67
	v_exp_f32_e32 v66, v66
	v_mul_f32_e32 v67, v173, v67
	v_mul_f32_e32 v66, v174, v66
	v_mul_f32_e32 v68, v59, v67
	v_mul_f32_e32 v73, v63, v66
	v_cvt_pk_bf16_f32 v67, v67, s0
	v_cvt_pk_bf16_f32 v66, v66, s0
	ds_write_b16 v121, v67 offset:34816
	ds_write_b16 v121, v66 offset:52224
	v_mad_i64_i32 v[66:67], s[34:35], s30, v104, 0
	v_cvt_pk_bf16_f32 v68, v68, s0
	v_lshl_add_u64 v[66:67], v[66:67], 1, v[60:61]
	global_store_short v[66:67], v68, off
	v_add_f32_e32 v66, v180, v203
	v_sub_f32_e32 v67, v66, v62
	v_sub_f32_e32 v66, v62, v66
	v_mul_f32_e32 v67, 0x3fb8aa3b, v67
	v_mul_f32_e32 v66, 0x3fb8aa3b, v66
	v_exp_f32_e32 v67, v67
	v_exp_f32_e32 v66, v66
	v_mul_f32_e32 v67, v176, v67
	v_mul_f32_e32 v66, v177, v66
	v_mul_f32_e32 v68, v59, v67
	v_mul_f32_e32 v127, v63, v66
	v_cvt_pk_bf16_f32 v67, v67, s0
	v_cvt_pk_bf16_f32 v66, v66, s0
	ds_write_b16 v123, v67 offset:34816
	ds_write_b16 v123, v66 offset:52224
	v_mad_i64_i32 v[66:67], s[34:35], s30, v106, 0
	v_cvt_pk_bf16_f32 v68, v68, s0
	v_lshl_add_u64 v[66:67], v[66:67], 1, v[60:61]
	global_store_short v[66:67], v68, off
	v_add_f32_e32 v66, v181, v203
	v_sub_f32_e32 v67, v66, v62
	v_sub_f32_e32 v66, v62, v66
	v_mul_f32_e32 v67, 0x3fb8aa3b, v67
	v_mul_f32_e32 v66, 0x3fb8aa3b, v66
	v_exp_f32_e32 v67, v67
	v_exp_f32_e32 v66, v66
	v_mul_f32_e32 v67, v178, v67
	v_mul_f32_e32 v66, v179, v66
	v_mul_f32_e32 v68, v59, v67
	v_mul_f32_e32 v129, v63, v66
	v_cvt_pk_bf16_f32 v67, v67, s0
	v_cvt_pk_bf16_f32 v66, v66, s0
	ds_write_b16 v125, v67 offset:34816
	ds_write_b16 v125, v66 offset:52224
	v_mad_i64_i32 v[66:67], s[34:35], s30, v108, 0
	v_cvt_pk_bf16_f32 v68, v68, s0
	v_lshl_add_u64 v[66:67], v[66:67], 1, v[60:61]
	global_store_short v[66:67], v68, off
	v_add_f32_e32 v66, v184, v203
	v_sub_f32_e32 v67, v66, v62
	v_sub_f32_e32 v66, v62, v66
	v_mul_f32_e32 v67, 0x3fb8aa3b, v67
	v_mul_f32_e32 v66, 0x3fb8aa3b, v66
	v_exp_f32_e32 v67, v67
	v_exp_f32_e32 v66, v66
	v_mul_f32_e32 v67, v182, v67
	v_mul_f32_e32 v66, v183, v66
	v_mul_f32_e32 v68, v59, v67
	v_mul_f32_e32 v131, v63, v66
	v_cvt_pk_bf16_f32 v67, v67, s0
	v_cvt_pk_bf16_f32 v66, v66, s0
	ds_write_b16 v142, v67 offset:34816
	ds_write_b16 v142, v66 offset:52224
	v_mad_i64_i32 v[66:67], s[34:35], s30, v110, 0
	v_cvt_pk_bf16_f32 v68, v68, s0
	v_lshl_add_u64 v[66:67], v[66:67], 1, v[60:61]
	global_store_short v[66:67], v68, off
	v_add_f32_e32 v66, v187, v203
	v_sub_f32_e32 v67, v66, v62
	v_sub_f32_e32 v66, v62, v66
	v_mul_f32_e32 v67, 0x3fb8aa3b, v67
	v_mul_f32_e32 v66, 0x3fb8aa3b, v66
	v_exp_f32_e32 v67, v67
	v_exp_f32_e32 v66, v66
	v_mul_f32_e32 v67, v185, v67
	v_mul_f32_e32 v66, v186, v66
	v_mul_f32_e32 v68, v59, v67
	v_mul_f32_e32 v133, v63, v66
	v_cvt_pk_bf16_f32 v67, v67, s0
	v_cvt_pk_bf16_f32 v66, v66, s0
	ds_write_b16 v143, v67 offset:34816
	ds_write_b16 v143, v66 offset:52224
	v_mad_i64_i32 v[66:67], s[34:35], s30, v112, 0
	v_cvt_pk_bf16_f32 v68, v68, s0
; __device__ __forceinline__ unsigned pk2(float lo, float hi) { f32x2 v = {lo, hi}; hbf2 b = __builtin_convertvector(v, hbf2); return __builtin_bit_cast(unsigned, b); }
; __device__ __forceinline__ bf16_t f2bf(float f) { return (bf16_t)(pk2(f, 0.f) & 0xffffu); }
; __device__ __forceinline__ float fexp(float x) { return __builtin_amdgcn_exp2f(x * 1.4426950408889634f); }
; __device__ __forceinline__ void hgrn_a(unsigned char* lds, const Params& p, int jl, bf16_t* proj, bf16_t* mix, float* dbuf, bf16_t* scr, float* useg, float* dseg, int blk, int G, int tid) {
;     ...
;             for (int i = 0; i < 16; ++i) { const int tok = tg * 16 + i; const float bt = off + cum[i];
;                 const float e1 = fexp(bt - bref), e2 = fexp(bref - bt);
;                 const float qt = qs[i] * e1, kt2 = kk[i] * e2, qh = qt * eref; kh[i] = kt2 * eend;
;                 QT[tok * 136 + c] = f2bf(qt); KTL[tok * 136 + c] = f2bf(kt2); qd[(size_t)tok * dstride + c] = f2bf(qh); }
;             { u32x4 w0, w1; w0.x = pk2(kh[0], kh[1]); w0.y = pk2(kh[2], kh[3]); w0.z = pk2(kh[4], kh[5]); w0.w = pk2(kh[6], kh[7]);
;               w1.x = pk2(kh[8], kh[9]); w1.y = pk2(kh[10], kh[11]); w1.z = pk2(kh[12], kh[13]); w1.w = pk2(kh[14], kh[15]);
;               bf16_t* kp = kd + (size_t)(c >> 1) * dstride + (c & 1) * 64 + tg * 16; *(u32x4*)kp = w0; *(u32x4*)(kp + 8) = w1;
;               *(u32x4*)(KHT + c * 72 + tg * 16) = w0; *(u32x4*)(KHT + c * 72 + tg * 16 + 8) = w1; }
;             if (tg == 0) { const float dd = fexp(bend); dbuf[(size_t)didx * DM + ch] = dd; DLS[c] = dd; bsum += bend; }
	v_lshl_add_u64 v[66:67], v[66:67], 1, v[60:61]
	global_store_short v[66:67], v68, off
	v_add_f32_e32 v66, v192, v203
	v_sub_f32_e32 v67, v66, v62
	v_sub_f32_e32 v66, v62, v66
	v_mul_f32_e32 v67, 0x3fb8aa3b, v67
	v_mul_f32_e32 v66, 0x3fb8aa3b, v66
	v_exp_f32_e32 v67, v67
	v_exp_f32_e32 v66, v66
	v_mul_f32_e32 v67, v188, v67
	v_mul_f32_e32 v66, v189, v66
	v_mul_f32_e32 v68, v59, v67
	v_mul_f32_e32 v135, v63, v66
	v_cvt_pk_bf16_f32 v67, v67, s0
	v_cvt_pk_bf16_f32 v66, v66, s0
	ds_write_b16 v144, v67 offset:34816
	ds_write_b16 v144, v66 offset:52224
	v_mad_i64_i32 v[66:67], s[34:35], s30, v114, 0
	v_cvt_pk_bf16_f32 v68, v68, s0
	v_lshl_add_u64 v[66:67], v[66:67], 1, v[60:61]
	global_store_short v[66:67], v68, off
	v_add_f32_e32 v66, v203, v193
	v_sub_f32_e32 v67, v66, v62
	v_sub_f32_e32 v66, v62, v66
	v_mul_f32_e32 v67, 0x3fb8aa3b, v67
	v_mul_f32_e32 v66, 0x3fb8aa3b, v66
	v_exp_f32_e32 v67, v67
	v_exp_f32_e32 v66, v66
	v_mul_f32_e32 v67, v190, v67
	v_mul_f32_e32 v66, v191, v66
	v_mul_f32_e32 v68, v59, v67
	v_mul_f32_e32 v137, v63, v66
	v_cvt_pk_bf16_f32 v67, v67, s0
	v_cvt_pk_bf16_f32 v66, v66, s0
	ds_write_b16 v145, v67 offset:34816
	ds_write_b16 v145, v66 offset:52224
	v_mad_i64_i32 v[66:67], s[34:35], s30, v116, 0
	v_cvt_pk_bf16_f32 v68, v68, s0
	v_lshl_add_u64 v[66:67], v[66:67], 1, v[60:61]
	global_store_short v[66:67], v68, off
	v_add_f32_e32 v66, v203, v196
	v_sub_f32_e32 v67, v66, v62
	v_sub_f32_e32 v66, v62, v66
	v_mul_f32_e32 v67, 0x3fb8aa3b, v67
	v_mul_f32_e32 v66, 0x3fb8aa3b, v66
	v_exp_f32_e32 v67, v67
	v_exp_f32_e32 v66, v66
	v_mul_f32_e32 v67, v194, v67
	v_mul_f32_e32 v66, v195, v66
	v_mul_f32_e32 v68, v59, v67
	v_mul_f32_e32 v152, v63, v66
	v_cvt_pk_bf16_f32 v67, v67, s0
	v_cvt_pk_bf16_f32 v66, v66, s0
	ds_write_b16 v146, v67 offset:34816
	ds_write_b16 v146, v66 offset:52224
	v_mad_i64_i32 v[66:67], s[34:35], s30, v118, 0
	v_cvt_pk_bf16_f32 v68, v68, s0
	v_lshl_add_u64 v[66:67], v[66:67], 1, v[60:61]
	global_store_short v[66:67], v68, off
	v_add_f32_e32 v66, v203, v199
	v_sub_f32_e32 v67, v66, v62
	v_sub_f32_e32 v66, v62, v66
	v_mul_f32_e32 v67, 0x3fb8aa3b, v67
	v_mul_f32_e32 v66, 0x3fb8aa3b, v66
	v_exp_f32_e32 v67, v67
	v_exp_f32_e32 v66, v66
	v_mul_f32_e32 v67, v197, v67
	v_mul_f32_e32 v66, v198, v66
	v_mul_f32_e32 v68, v59, v67
	v_mul_f32_e32 v153, v63, v66
	v_cvt_pk_bf16_f32 v67, v67, s0
	v_cvt_pk_bf16_f32 v66, v66, s0
	ds_write_b16 v147, v67 offset:34816
	ds_write_b16 v147, v66 offset:52224
	v_mad_i64_i32 v[66:67], s[34:35], s30, v120, 0
	v_cvt_pk_bf16_f32 v68, v68, s0
	v_lshl_add_u64 v[66:67], v[66:67], 1, v[60:61]
	global_store_short v[66:67], v68, off
	v_add_f32_e32 v66, v203, v202
	v_sub_f32_e32 v67, v66, v62
	v_sub_f32_e32 v62, v62, v66
	v_mul_f32_e32 v67, 0x3fb8aa3b, v67
	v_mul_f32_e32 v62, 0x3fb8aa3b, v62
	v_exp_f32_e32 v67, v67
	v_exp_f32_e32 v62, v62
	v_mul_f32_e32 v66, v200, v67
	v_mul_f32_e32 v62, v201, v62
	v_mul_f32_e32 v67, v63, v62
	v_cvt_pk_bf16_f32 v63, v66, s0
	v_cvt_pk_bf16_f32 v62, v62, s0
	v_mul_f32_e32 v59, v59, v66
	ds_write_b16 v158, v63 offset:34816
	ds_write_b16 v158, v62 offset:52224
	v_mad_i64_i32 v[62:63], s[34:35], s30, v122, 0
	v_cvt_pk_bf16_f32 v59, v59, s0
	v_lshl_add_u64 v[60:61], v[62:63], 1, v[60:61]
	global_store_short v[60:61], v59, off
	v_mul_u32_u24_e32 v59, s30, v97
	v_cvt_pk_bf16_f32 v61, v69, v70
	v_lshlrev_b32_e32 v68, 1, v59
	v_mov_b32_e32 v69, v1
	v_cvt_pk_bf16_f32 v60, v64, v65
	v_cvt_pk_bf16_f32 v64, v129, v131
	v_lshl_add_u64 v[68:69], s[24:25], 0, v[68:69]
	v_mov_b32_e32 v129, v1
	v_lshl_add_u64 v[68:69], v[68:69], 0, v[128:129]
	v_cvt_pk_bf16_f32 v62, v71, v72
	v_cvt_pk_bf16_f32 v63, v73, v127
	v_lshl_add_u64 v[68:69], v[90:91], 1, v[68:69]
	v_cvt_pk_bf16_f32 v65, v133, v135
	v_cvt_pk_bf16_f32 v66, v137, v152
	v_cvt_pk_bf16_f32 v67, v153, v67
	global_store_dwordx4 v[68:69], v[60:63], off
	global_store_dwordx4 v[68:69], v[64:67], off offset:16
	ds_write_b128 v99, v[60:63]
	ds_write_b128 v99, v[64:67] offset:16
	s_mov_b64 s[24:25], exec
	v_readlane_b32 s34, v255, 36
	v_readlane_b32 s35, v255, 37
	s_and_b64 s[34:35], s[24:25], s[34:35]
	s_mov_b64 exec, s[34:35]
	s_cbranch_execz .LBB0_255
	v_add_f32_e32 v167, v167, v58
	v_mul_f32_e32 v58, 0x3fb8aa3b, v58
	v_exp_f32_e32 v60, v58
	s_ashr_i32 s71, s70, 31
	s_lshl_b64 s[34:35], s[70:71], 13
	s_movk_i32 s71, 0x2000
	v_lshl_add_u64 v[58:59], v[138:139], 0, s[34:35]
	global_store_dword v[58:59], v60, off
	ds_write_b32 v105, v60

; #define MFMA16(a, b, c) __builtin_amdgcn_mfma_f32_16x16x32_bf16((a), (b), (c), 0, 0, 0)
; __device__ __forceinline__ void hgrn_b(unsigned char* lds, const Params& p, int jl, const bf16_t* proj, bf16_t* mix, const float* dbuf, const bf16_t* scr, const float* useg, const float* dseg, int blk, int G, int tid) {
;     ...
;             { bf16x8 sa[4];
; #pragma unroll
;               for (int k2 = 0; k2 < 4; ++k2) sa[k2] = pack8(S[2 * k2], S[2 * k2 + 1]);
; #pragma unroll
;               for (int th = 0; th < 2; ++th) { bf16x8 qfr[2][4];
; #pragma unroll
;                   for (int t2 = 0; t2 < 2; ++t2)
; #pragma unroll
;                       for (int k2 = 0; k2 < 4; ++k2) { const bf16_t* qp = qh + ((th * 2 + t2) * 16 + fr) * 136 + k2 * 32 + fq * 4; qfr[t2][k2] = cat8(*(const bf16x4*)qp, *(const bf16x4*)(qp + 16)); }
;                   __builtin_amdgcn_sched_barrier(0);
; #pragma unroll
;                   for (int t2 = 0; t2 < 2; ++t2) oT[th * 2 + t2] = (f32x4){0.f, 0.f, 0.f, 0.f};
; #pragma unroll
;                   for (int k2 = 0; k2 < 4; ++k2)
; #pragma unroll
;                       for (int t2 = 0; t2 < 2; ++t2) oT[th * 2 + t2] = MFMA16(sa[k2], qfr[t2][k2], oT[th * 2 + t2]);
;                   __builtin_amdgcn_sched_barrier(0); } }
;             { bf16x8 vb[2];
; #pragma unroll
;               for (int ks = 0; ks < 2; ++ks) vb[ks] = *(const bf16x8*)(vt + (w * 16 + fr) * 72 + ks * 32 + fq * 8);
; #pragma unroll
;               for (int kh2 = 0; kh2 < 2; ++kh2) { bf16x8 kf[4][2]; f32x4 dv[4];
; #pragma unroll
;                   for (int k3 = 0; k3 < 4; ++k3) { dv[k3] = *(const f32x4*)(dl + (kh2 * 4 + k3) * 16 + fq * 4);
; #pragma unroll
;                       for (int ks = 0; ks < 2; ++ks) kf[k3][ks] = *(const bf16x8*)(kt + ((kh2 * 4 + k3) * 16 + fr) * 72 + ks * 32 + fq * 8); }
;                   __builtin_amdgcn_sched_barrier(0);
; #pragma unroll
;                   for (int k3 = 0; k3 < 4; ++k3) S[kh2 * 4 + k3] = S[kh2 * 4 + k3] * dv[k3];
; #pragma unroll
;                   for (int ks = 0; ks < 2; ++ks)
; #pragma unroll
;                       for (int k3 = 0; k3 < 4; ++k3) S[kh2 * 4 + k3] = MFMA16(kf[k3][ks], vb[ks], S[kh2 * 4 + k3]);
;                   __builtin_amdgcn_sched_barrier(0); } }
; #pragma unroll
;             for (int tt = 0; tt < 4; ++tt) { float ss = 0.f;
; #pragma unroll
.LBB0_412:
	s_or_b64 exec, exec, s[16:17]
	s_and_b32 s19, s19, 1
	s_mul_i32 s16, s19, 0x4400
	v_add3_u32 v0, v125, s16, v180
	v_add_u32_e32 v152, 0x1000, v0
	ds_read2_b64 v[68:71], v0 offset1:4
	ds_read2_b64 v[184:187], v0 offset0:8 offset1:12
	ds_read2_b64 v[188:191], v0 offset0:16 offset1:20
	ds_read2_b64 v[192:195], v0 offset0:24 offset1:28
	ds_read2_b64 v[196:199], v152 offset0:32 offset1:36
	ds_read2_b64 v[200:203], v152 offset0:40 offset1:44
	ds_read2_b64 v[204:207], v152 offset0:48 offset1:52
	ds_read2_b64 v[216:219], v152 offset0:56 offset1:60
	v_cvt_pk_bf16_f32 v72, v36, v37
	v_cvt_pk_bf16_f32 v73, v38, v39
	v_cvt_pk_bf16_f32 v74, v40, v41
	v_cvt_pk_bf16_f32 v75, v42, v43
	v_cvt_pk_bf16_f32 v76, v44, v45
	v_cvt_pk_bf16_f32 v77, v46, v47
	v_cvt_pk_bf16_f32 v78, v48, v49
	v_cvt_pk_bf16_f32 v79, v50, v51
	v_cvt_pk_bf16_f32 v166, v56, v57
	v_cvt_pk_bf16_f32 v167, v58, v59
	v_cvt_pk_bf16_f32 v164, v52, v53
	v_cvt_pk_bf16_f32 v165, v54, v55
	v_cvt_pk_bf16_f32 v220, v60, v61
	v_cvt_pk_bf16_f32 v221, v62, v63
	v_cvt_pk_bf16_f32 v222, v64, v65
	v_cvt_pk_bf16_f32 v223, v66, v67
	s_waitcnt lgkmcnt(7)
	v_mfma_f32_16x16x32_bf16 v[68:71], v[72:75], v[68:71], 0
	s_waitcnt lgkmcnt(3)
	v_mfma_f32_16x16x32_bf16 v[196:199], v[72:75], v[196:199], 0
	v_mfma_f32_16x16x32_bf16 v[68:71], v[76:79], v[184:187], v[68:71]
	s_waitcnt lgkmcnt(2)
	v_mfma_f32_16x16x32_bf16 v[184:187], v[76:79], v[200:203], v[196:199]
	v_mfma_f32_16x16x32_bf16 v[68:71], v[164:167], v[188:191], v[68:71]
	s_waitcnt lgkmcnt(1)
	v_mfma_f32_16x16x32_bf16 v[184:187], v[164:167], v[204:207], v[184:187]
	v_mfma_f32_16x16x32_bf16 v[188:191], v[220:223], v[192:195], v[68:71]
	s_waitcnt lgkmcnt(0)
	v_mfma_f32_16x16x32_bf16 v[68:71], v[220:223], v[216:219], v[184:187]
	v_add_u32_e32 v152, 0x2000, v0
	v_add_u32_e32 v0, 0x3000, v0
	s_nop 2
	ds_read2_b64 v[184:187], v152 offset0:64 offset1:68
	ds_read2_b64 v[192:195], v152 offset0:72 offset1:76
	ds_read2_b64 v[196:199], v152 offset0:80 offset1:84
	ds_read2_b64 v[200:203], v152 offset0:88 offset1:92
	ds_read2_b64 v[204:207], v0 offset0:96 offset1:100
	ds_read2_b64 v[216:219], v0 offset0:104 offset1:108
	ds_read2_b64 v[224:227], v0 offset0:112 offset1:116
	ds_read2_b64 v[228:231], v0 offset0:120 offset1:124
	s_waitcnt lgkmcnt(7)
	v_mfma_f32_16x16x32_bf16 v[184:187], v[72:75], v[184:187], 0
	s_waitcnt lgkmcnt(3)
	v_mfma_f32_16x16x32_bf16 v[72:75], v[72:75], v[204:207], 0
	v_mfma_f32_16x16x32_bf16 v[184:187], v[76:79], v[192:195], v[184:187]
	s_waitcnt lgkmcnt(2)
	v_mfma_f32_16x16x32_bf16 v[72:75], v[76:79], v[216:219], v[72:75]
	v_mfma_f32_16x16x32_bf16 v[76:79], v[164:167], v[196:199], v[184:187]
	s_waitcnt lgkmcnt(1)
	v_mfma_f32_16x16x32_bf16 v[72:75], v[164:167], v[224:227], v[72:75]
	v_mfma_f32_16x16x32_bf16 v[76:79], v[220:223], v[200:203], v[76:79]
	s_waitcnt lgkmcnt(0)
	v_mfma_f32_16x16x32_bf16 v[72:75], v[220:223], v[228:231], v[72:75]
	s_mul_i32 s16, s19, 0x4800
	v_add_u32_e32 v0, s16, v170
	v_add3_u32 v152, v172, s16, v181
	ds_read_b128 v[164:167], v0
	ds_read_b128 v[184:187], v0 offset:64
	v_lshl_add_u32 v0, s19, 9, v171
	ds_read_b128 v[192:195], v152 offset:34816
	ds_read_b128 v[196:199], v152 offset:34880
	ds_read_b128 v[200:203], v0
	ds_read_b128 v[204:207], v0 offset:64
	ds_read_b128 v[216:219], v152 offset:37120
	ds_read_b128 v[220:223], v152 offset:37184
	ds_read_b128 v[224:227], v152 offset:39424
	ds_read_b128 v[228:231], v152 offset:39488
	ds_read_b128 v[232:235], v0 offset:128
	ds_read_b128 v[236:239], v0 offset:192
	ds_read_b128 v[240:243], v152 offset:41728
	ds_read_b128 v[244:247], v152 offset:41792
	s_waitcnt lgkmcnt(9)
	v_pk_mul_f32 v[36:37], v[36:37], v[200:201]
	v_pk_mul_f32 v[38:39], v[38:39], v[202:203]
	s_waitcnt lgkmcnt(8)
	v_pk_mul_f32 v[40:41], v[40:41], v[204:205]
	v_pk_mul_f32 v[42:43], v[42:43], v[206:207]
	s_waitcnt lgkmcnt(3)
	v_pk_mul_f32 v[44:45], v[44:45], v[232:233]
	v_pk_mul_f32 v[46:47], v[46:47], v[234:235]
	s_waitcnt lgkmcnt(2)
	v_pk_mul_f32 v[48:49], v[48:49], v[236:237]
	v_pk_mul_f32 v[50:51], v[50:51], v[238:239]
	v_mfma_f32_16x16x32_bf16 v[36:39], v[192:195], v[164:167], v[36:39]
	v_mfma_f32_16x16x32_bf16 v[40:43], v[216:219], v[164:167], v[40:43]
	v_mfma_f32_16x16x32_bf16 v[44:47], v[224:227], v[164:167], v[44:47]
	s_waitcnt lgkmcnt(1)
	v_mfma_f32_16x16x32_bf16 v[48:51], v[240:243], v[164:167], v[48:51]
	v_mfma_f32_16x16x32_bf16 v[36:39], v[196:199], v[184:187], v[36:39]
	v_mfma_f32_16x16x32_bf16 v[40:43], v[220:223], v[184:187], v[40:43]
	v_mfma_f32_16x16x32_bf16 v[44:47], v[228:231], v[184:187], v[44:47]
	s_waitcnt lgkmcnt(0)
	v_mfma_f32_16x16x32_bf16 v[48:51], v[244:247], v[184:187], v[48:51]
	ds_read_b128 v[192:195], v152 offset:44032
	ds_read_b128 v[196:199], v152 offset:44096
	ds_read_b128 v[200:203], v0 offset:256
	ds_read_b128 v[204:207], v0 offset:320
	ds_read_b128 v[216:219], v152 offset:46336
	ds_read_b128 v[220:223], v152 offset:46400
	ds_read_b128 v[224:227], v152 offset:48640
	ds_read_b128 v[228:231], v152 offset:48704
	ds_read_b128 v[232:235], v0 offset:384
	ds_read_b128 v[236:239], v0 offset:448
	ds_read_b128 v[240:243], v152 offset:50944
	ds_read_b128 v[244:247], v152 offset:51008
	s_waitcnt lgkmcnt(9)
	v_pk_mul_f32 v[52:53], v[52:53], v[200:201]
	v_pk_mul_f32 v[54:55], v[54:55], v[202:203]
	s_waitcnt lgkmcnt(8)
	v_pk_mul_f32 v[56:57], v[56:57], v[204:205]
	v_pk_mul_f32 v[58:59], v[58:59], v[206:207]
	s_waitcnt lgkmcnt(3)
	v_pk_mul_f32 v[60:61], v[60:61], v[232:233]
	v_pk_mul_f32 v[62:63], v[62:63], v[234:235]
	s_waitcnt lgkmcnt(2)
	v_pk_mul_f32 v[64:65], v[64:65], v[236:237]
	v_pk_mul_f32 v[66:67], v[66:67], v[238:239]
	v_mfma_f32_16x16x32_bf16 v[52:55], v[192:195], v[164:167], v[52:55]
	v_mfma_f32_16x16x32_bf16 v[56:59], v[216:219], v[164:167], v[56:59]
	v_mfma_f32_16x16x32_bf16 v[60:63], v[224:227], v[164:167], v[60:63]
	s_waitcnt lgkmcnt(1)
	v_mfma_f32_16x16x32_bf16 v[64:67], v[240:243], v[164:167], v[64:67]
	v_mfma_f32_16x16x32_bf16 v[52:55], v[196:199], v[184:187], v[52:55]
	v_mfma_f32_16x16x32_bf16 v[56:59], v[220:223], v[184:187], v[56:59]
	v_mfma_f32_16x16x32_bf16 v[60:63], v[228:231], v[184:187], v[60:63]
	s_waitcnt lgkmcnt(0)
	v_mfma_f32_16x16x32_bf16 v[64:67], v[244:247], v[184:187], v[64:67]
	s_waitcnt vmcnt(3)
	v_lshlrev_b32_e32 v152, 16, v162
	v_and_b32_e32 v153, 0xffff0000, v162
	v_pk_add_f32 v[166:167], v[188:189], v[152:153]
	v_lshlrev_b32_e32 v162, 16, v163
	v_and_b32_e32 v163, 0xffff0000, v163
	v_pk_mul_f32 v[152:153], v[166:167], v[166:167]
	v_pk_add_f32 v[168:169], v[190:191], v[162:163]
	v_add_f32_e32 v0, v152, v153
	v_pk_mul_f32 v[162:163], v[168:169], v[168:169]
	s_nop 0
	v_add_f32_e32 v0, v162, v0
	v_add_f32_e32 v0, v163, v0
	v_mov_b32_e32 v152, v0
	s_nop 1
	v_permlane16_swap_b32_e32 v152, v0
	v_add_f32_e32 v0, v0, v152
	v_mov_b32_e32 v162, v0
	s_nop 1
	v_permlane32_swap_b32_e32 v162, v0
	v_add_f32_e32 v0, v0, v162
	s_and_saveexec_b64 s[16:17], s[4:5]
	s_cbranch_execz .LBB0_414
	ds_write_b32 v176, v0
; __device__ __forceinline__ void hgrn_b(unsigned char* lds, const Params& p, int jl, const bf16_t* proj, bf16_t* mix, const float* dbuf, const bf16_t* scr, const float* useg, const float* dseg, int blk, int G, int tid) {
;     ...
;             for (int tt = 0; tt < 4; ++tt) { float ss = 0.f;
; #pragma unroll
;                 for (int j = 0; j < 4; ++j) { const unsigned wv = oin[tt][j >> 1]; const float oi = __uint_as_float((j & 1) ? (wv & 0xffff0000u) : (wv << 16)); const float ov = oT[tt][j] + oi; oT[tt][j] = ov; ss += ov * ov; }
;                 ss += __shfl_xor(ss, 16); ss += __shfl_xor(ss, 32);
;                 if (fq == 0) PART[(tt * 16 + fr) * 8 + w] = ss; }
.LBB0_414:
	s_or_b64 exec, exec, s[16:17]
	s_waitcnt vmcnt(1)
	v_lshlrev_b32_e32 v152, 16, v158
	v_and_b32_e32 v153, 0xffff0000, v158
	v_pk_add_f32 v[164:165], v[68:69], v[152:153]
	v_lshlrev_b32_e32 v152, 16, v159
	v_and_b32_e32 v153, 0xffff0000, v159
	v_pk_mul_f32 v[68:69], v[164:165], v[164:165]
	s_waitcnt lgkmcnt(0)
	v_pk_add_f32 v[162:163], v[70:71], v[152:153]
	v_add_f32_e32 v0, v68, v69
	v_pk_mul_f32 v[70:71], v[162:163], v[162:163]
	s_nop 0
	v_add_f32_e32 v0, v70, v0
	v_add_f32_e32 v0, v71, v0
	v_mov_b32_e32 v68, v0
	s_nop 1
	v_permlane16_swap_b32_e32 v68, v0
	v_add_f32_e32 v0, v0, v68
	v_mov_b32_e32 v68, v0
	s_nop 1
	v_permlane32_swap_b32_e32 v68, v0
	v_add_f32_e32 v0, v0, v68
	s_and_saveexec_b64 s[16:17], s[4:5]
	s_cbranch_execz .LBB0_416
	ds_write_b32 v176, v0 offset:512
.LBB0_416:
	s_or_b64 exec, exec, s[16:17]
	s_waitcnt lgkmcnt(0)
	v_lshlrev_b32_e32 v68, 16, v146
	v_and_b32_e32 v69, 0xffff0000, v146
	v_pk_add_f32 v[158:159], v[76:77], v[68:69]
	v_lshlrev_b32_e32 v70, 16, v147
	v_and_b32_e32 v71, 0xffff0000, v147
	v_pk_mul_f32 v[68:69], v[158:159], v[158:159]
	v_pk_add_f32 v[76:77], v[78:79], v[70:71]
	v_add_f32_e32 v0, v68, v69
	v_pk_mul_f32 v[70:71], v[76:77], v[76:77]
	s_nop 0
	v_add_f32_e32 v0, v70, v0
	v_add_f32_e32 v0, v71, v0
	v_mov_b32_e32 v68, v0
	s_nop 1
	v_permlane16_swap_b32_e32 v68, v0
	v_add_f32_e32 v0, v0, v68
	v_mov_b32_e32 v68, v0
	s_nop 1
	v_permlane32_swap_b32_e32 v68, v0
	v_add_f32_e32 v0, v0, v68
	s_and_saveexec_b64 s[16:17], s[4:5]
	s_cbranch_execz .LBB0_418
	ds_write_b32 v176, v0 offset:1024
.LBB0_418:
	s_or_b64 exec, exec, s[16:17]
	s_waitcnt lgkmcnt(0)
	v_lshlrev_b32_e32 v68, 16, v160
	v_and_b32_e32 v69, 0xffff0000, v160
	v_pk_add_f32 v[70:71], v[72:73], v[68:69]
	v_lshlrev_b32_e32 v68, 16, v161
	v_and_b32_e32 v69, 0xffff0000, v161
	v_pk_mul_f32 v[72:73], v[70:71], v[70:71]
	v_pk_add_f32 v[68:69], v[74:75], v[68:69]
	v_add_f32_e32 v0, v72, v73
	v_pk_mul_f32 v[74:75], v[68:69], v[68:69]
	s_nop 0
	v_add_f32_e32 v0, v74, v0
	v_add_f32_e32 v0, v75, v0
	v_mov_b32_e32 v72, v0
	s_nop 1
	v_permlane16_swap_b32_e32 v72, v0
	v_add_f32_e32 v0, v0, v72
	v_mov_b32_e32 v72, v0
	s_nop 1
	v_permlane32_swap_b32_e32 v72, v0
	v_add_f32_e32 v0, v0, v72
	s_and_saveexec_b64 s[16:17], s[4:5]
	s_cbranch_execz .LBB0_420
	ds_write_b32 v176, v0 offset:1536
